# v95 + EP_RESID epilogues (phases 5,7,12,14): bf16 output copy staged in free VGPRs and stored as 16-byte stores via v_permlane16_swap; prefetch vmcnt counts lowered to the new store count
# speedup vs baseline: 1.0142x; 1.0055x over previous
.LBB0_531:
	s_mul_i32 s43, s1, 0x6000
	s_add_i32 s50, s43, 0xffffa000
	s_cmp_lg_u32 s1, 0
	s_cselect_b32 s50, s50, 0xc000
	v_add_u32_e32 v150, s50, v143
	v_lshl_add_u64 v[146:147], v[138:139], 0, s[48:49]
	v_readfirstlane_b32 s50, v150
	v_add_u32_e32 v151, 0x1000, v150
	v_lshl_add_u64 v[148:149], v[146:147], 0, s[24:25]
	s_mov_b32 m0, s50
	v_readfirstlane_b32 s50, v151
	v_add_u32_e32 v151, 0x2000, v150
	s_waitcnt vmcnt(6)
	s_barrier
	global_load_lds_dwordx4 v[148:149], off
	v_lshl_add_u64 v[148:149], v[146:147], 0, s[26:27]
	s_mov_b32 m0, s50
	v_readfirstlane_b32 s50, v151
	global_load_lds_dwordx4 v[148:149], off
	v_lshl_add_u64 v[148:149], v[146:147], 0, s[28:29]
	s_mov_b32 m0, s50
	v_lshl_add_u64 v[146:147], v[146:147], 0, s[30:31]
	global_load_lds_dwordx4 v[148:149], off
	v_add_u32_e32 v148, 0x3000, v150
	v_add_u32_e32 v151, 0x4000, v150
	v_readfirstlane_b32 s50, v148
	s_mov_b32 m0, s50
	v_readfirstlane_b32 s50, v151
	global_load_lds_dwordx4 v[146:147], off
	v_lshl_add_u64 v[146:147], v[136:137], 0, s[48:49]
	v_lshl_add_u64 v[148:149], v[146:147], 0, s[34:35]
	s_mov_b32 m0, s50
	v_lshl_add_u64 v[146:147], v[146:147], 0, s[44:45]
	global_load_lds_dwordx4 v[148:149], off
	v_add_u32_e32 v148, 0x5000, v150
	s_add_i32 s43, s43, 0
	v_readfirstlane_b32 s50, v148
	s_mov_b32 m0, s50
	v_add3_u32 v158, s43, v142, v145
	global_load_lds_dwordx4 v[146:147], off
	v_add3_u32 v178, s43, v144, v145
	ds_read_b128 v[146:149], v158 offset:16384
	ds_read_b128 v[150:153], v158 offset:17408
	ds_read_b128 v[154:157], v158 offset:18432
	ds_read_b128 v[158:161], v158 offset:19456
	ds_read_b128 v[162:165], v178
	ds_read_b128 v[166:169], v178 offset:1024
	ds_read_b128 v[170:173], v178 offset:2048
	ds_read_b128 v[174:177], v178 offset:3072
	s_setprio 1
	s_waitcnt lgkmcnt(0)
	v_mfma_f32_16x16x32_bf16 v[126:129], v[146:149], v[162:165], v[126:129]
	v_mfma_f32_16x16x32_bf16 v[122:125], v[150:153], v[162:165], v[122:125]
	v_mfma_f32_16x16x32_bf16 v[118:121], v[154:157], v[162:165], v[118:121]
	v_mfma_f32_16x16x32_bf16 v[114:117], v[158:161], v[162:165], v[114:117]
	v_mfma_f32_16x16x32_bf16 v[110:113], v[146:149], v[166:169], v[110:113]
	v_mfma_f32_16x16x32_bf16 v[106:109], v[150:153], v[166:169], v[106:109]
	v_mfma_f32_16x16x32_bf16 v[102:105], v[154:157], v[166:169], v[102:105]
	v_mfma_f32_16x16x32_bf16 v[98:101], v[158:161], v[166:169], v[98:101]
	v_mfma_f32_16x16x32_bf16 v[94:97], v[146:149], v[170:173], v[94:97]
	v_mfma_f32_16x16x32_bf16 v[90:93], v[150:153], v[170:173], v[90:93]
	v_mfma_f32_16x16x32_bf16 v[86:89], v[154:157], v[170:173], v[86:89]
	v_mfma_f32_16x16x32_bf16 v[82:85], v[158:161], v[170:173], v[82:85]
	v_mfma_f32_16x16x32_bf16 v[78:81], v[146:149], v[174:177], v[78:81]
	v_mfma_f32_16x16x32_bf16 v[74:77], v[150:153], v[174:177], v[74:77]
	v_mfma_f32_16x16x32_bf16 v[70:73], v[154:157], v[174:177], v[70:73]
	v_mfma_f32_16x16x32_bf16 v[66:69], v[158:161], v[174:177], v[66:69]
	s_setprio 0
	ds_read_b128 v[162:165], v178 offset:4096
	ds_read_b128 v[166:169], v178 offset:5120
	ds_read_b128 v[170:173], v178 offset:6144
	ds_read_b128 v[174:177], v178 offset:7168
	s_setprio 1
	s_waitcnt lgkmcnt(0)
	v_mfma_f32_16x16x32_bf16 v[62:65], v[146:149], v[162:165], v[62:65]
	v_mfma_f32_16x16x32_bf16 v[58:61], v[150:153], v[162:165], v[58:61]
	v_mfma_f32_16x16x32_bf16 v[54:57], v[154:157], v[162:165], v[54:57]
	v_mfma_f32_16x16x32_bf16 v[50:53], v[158:161], v[162:165], v[50:53]
	v_mfma_f32_16x16x32_bf16 v[46:49], v[146:149], v[166:169], v[46:49]
	v_mfma_f32_16x16x32_bf16 v[42:45], v[150:153], v[166:169], v[42:45]
	v_mfma_f32_16x16x32_bf16 v[38:41], v[154:157], v[166:169], v[38:41]
	v_mfma_f32_16x16x32_bf16 v[34:37], v[158:161], v[166:169], v[34:37]
	v_mfma_f32_16x16x32_bf16 v[30:33], v[146:149], v[170:173], v[30:33]
	v_mfma_f32_16x16x32_bf16 v[26:29], v[150:153], v[170:173], v[26:29]
	v_mfma_f32_16x16x32_bf16 v[22:25], v[154:157], v[170:173], v[22:25]
	v_mfma_f32_16x16x32_bf16 v[18:21], v[158:161], v[170:173], v[18:21]
	v_mfma_f32_16x16x32_bf16 v[14:17], v[146:149], v[174:177], v[14:17]
	v_mfma_f32_16x16x32_bf16 v[10:13], v[150:153], v[174:177], v[10:13]
	v_mfma_f32_16x16x32_bf16 v[6:9], v[154:157], v[174:177], v[6:9]
	v_mfma_f32_16x16x32_bf16 v[2:5], v[158:161], v[174:177], v[2:5]
	s_setprio 0
	s_add_i32 s43, s1, 1
	s_cmp_lg_u32 s1, 2
	s_cselect_b32 s1, s43, 0
	s_add_u32 s48, s48, 64
	s_addc_u32 s49, s49, 0
	s_cmpk_eq_i32 s48, 0x780
	s_cbranch_scc0 .LBB0_531
	v_add3_u32 v170, 0, v142, v145
	v_add3_u32 v174, 0, v144, v145
	s_waitcnt vmcnt(6)
	s_barrier
	ds_read_b128 v[136:139], v170 offset:16384
	ds_read_b128 v[146:149], v170 offset:17408
	ds_read_b128 v[150:153], v170 offset:18432
	ds_read_b128 v[154:157], v170 offset:19456
	ds_read_b128 v[142:145], v174
	ds_read_b128 v[158:161], v174 offset:1024
	ds_read_b128 v[162:165], v174 offset:2048
	ds_read_b128 v[166:169], v174 offset:3072
	s_lshl_b64 s[46:47], s[46:47], 8
	s_setprio 1
	s_waitcnt lgkmcnt(0)
	v_mfma_f32_16x16x32_bf16 v[122:125], v[146:149], v[142:145], v[122:125]
	v_mfma_f32_16x16x32_bf16 v[118:121], v[150:153], v[142:145], v[118:121]
	v_mfma_f32_16x16x32_bf16 v[114:117], v[154:157], v[142:145], v[114:117]
	v_mfma_f32_16x16x32_bf16 v[110:113], v[136:139], v[158:161], v[110:113]
	v_mfma_f32_16x16x32_bf16 v[106:109], v[146:149], v[158:161], v[106:109]
	v_mfma_f32_16x16x32_bf16 v[102:105], v[150:153], v[158:161], v[102:105]
	v_mfma_f32_16x16x32_bf16 v[98:101], v[154:157], v[158:161], v[98:101]
	v_mfma_f32_16x16x32_bf16 v[94:97], v[136:139], v[162:165], v[94:97]
	v_mfma_f32_16x16x32_bf16 v[90:93], v[146:149], v[162:165], v[90:93]
	v_mfma_f32_16x16x32_bf16 v[86:89], v[150:153], v[162:165], v[86:89]
	v_mfma_f32_16x16x32_bf16 v[82:85], v[154:157], v[162:165], v[82:85]
	v_mfma_f32_16x16x32_bf16 v[78:81], v[136:139], v[166:169], v[78:81]
	v_mfma_f32_16x16x32_bf16 v[74:77], v[146:149], v[166:169], v[74:77]
	v_mfma_f32_16x16x32_bf16 v[70:73], v[150:153], v[166:169], v[70:73]
	v_mfma_f32_16x16x32_bf16 v[66:69], v[154:157], v[166:169], v[66:69]
	v_mfma_f32_16x16x32_bf16 v[126:129], v[136:139], v[142:145], v[126:129]
	s_setprio 0
	ds_read_b128 v[142:145], v174 offset:4096
	ds_read_b128 v[158:161], v174 offset:5120
	ds_read_b128 v[162:165], v174 offset:6144
	ds_read_b128 v[166:169], v174 offset:7168
	s_setprio 1
	s_waitcnt lgkmcnt(0)
	v_mfma_f32_16x16x32_bf16 v[62:65], v[136:139], v[142:145], v[62:65]
	v_mfma_f32_16x16x32_bf16 v[58:61], v[146:149], v[142:145], v[58:61]
	v_mfma_f32_16x16x32_bf16 v[54:57], v[150:153], v[142:145], v[54:57]
	v_mfma_f32_16x16x32_bf16 v[50:53], v[154:157], v[142:145], v[50:53]
	v_mfma_f32_16x16x32_bf16 v[46:49], v[136:139], v[158:161], v[46:49]
	v_mfma_f32_16x16x32_bf16 v[42:45], v[146:149], v[158:161], v[42:45]
	v_mfma_f32_16x16x32_bf16 v[38:41], v[150:153], v[158:161], v[38:41]
	v_mfma_f32_16x16x32_bf16 v[34:37], v[154:157], v[158:161], v[34:37]
	v_mfma_f32_16x16x32_bf16 v[30:33], v[136:139], v[162:165], v[30:33]
	v_mfma_f32_16x16x32_bf16 v[26:29], v[146:149], v[162:165], v[26:29]
	v_mfma_f32_16x16x32_bf16 v[22:25], v[150:153], v[162:165], v[22:25]
	v_mfma_f32_16x16x32_bf16 v[18:21], v[154:157], v[162:165], v[18:21]
	v_mfma_f32_16x16x32_bf16 v[14:17], v[136:139], v[166:169], v[14:17]
	v_mfma_f32_16x16x32_bf16 v[10:13], v[146:149], v[166:169], v[10:13]
	v_mfma_f32_16x16x32_bf16 v[6:9], v[150:153], v[166:169], v[6:9]
	v_mfma_f32_16x16x32_bf16 v[2:5], v[154:157], v[166:169], v[2:5]
	s_setprio 0
	s_waitcnt vmcnt(0)
	s_barrier
	ds_read_b128 v[136:139], v170 offset:40960
	ds_read_b128 v[142:145], v170 offset:41984
	ds_read_b128 v[146:149], v170 offset:43008
	ds_read_b128 v[150:153], v170 offset:44032
	ds_read_b128 v[154:157], v174 offset:24576
	ds_read_b128 v[158:161], v174 offset:25600
	ds_read_b128 v[162:165], v174 offset:26624
	ds_read_b128 v[166:169], v174 offset:27648
	s_setprio 1
	s_waitcnt lgkmcnt(0)
	v_mfma_f32_16x16x32_bf16 v[122:125], v[142:145], v[154:157], v[122:125]
	v_mfma_f32_16x16x32_bf16 v[110:113], v[136:139], v[158:161], v[110:113]
	v_mfma_f32_16x16x32_bf16 v[106:109], v[142:145], v[158:161], v[106:109]
	v_mfma_f32_16x16x32_bf16 v[102:105], v[146:149], v[158:161], v[102:105]
	v_mfma_f32_16x16x32_bf16 v[98:101], v[150:153], v[158:161], v[98:101]
	v_mfma_f32_16x16x32_bf16 v[94:97], v[136:139], v[162:165], v[94:97]
	v_mfma_f32_16x16x32_bf16 v[90:93], v[142:145], v[162:165], v[90:93]
	v_mfma_f32_16x16x32_bf16 v[86:89], v[146:149], v[162:165], v[86:89]
	v_mfma_f32_16x16x32_bf16 v[82:85], v[150:153], v[162:165], v[82:85]
	v_mfma_f32_16x16x32_bf16 v[78:81], v[136:139], v[166:169], v[78:81]
	v_mfma_f32_16x16x32_bf16 v[74:77], v[142:145], v[166:169], v[74:77]
	v_mfma_f32_16x16x32_bf16 v[70:73], v[146:149], v[166:169], v[70:73]
	v_mfma_f32_16x16x32_bf16 v[66:69], v[150:153], v[166:169], v[66:69]
	v_mfma_f32_16x16x32_bf16 v[126:129], v[136:139], v[154:157], v[126:129]
	v_mfma_f32_16x16x32_bf16 v[170:173], v[146:149], v[154:157], v[118:121]
	v_mfma_f32_16x16x32_bf16 v[154:157], v[150:153], v[154:157], v[114:117]
	s_setprio 0
	s_nop 1
	ds_read_b128 v[114:117], v174 offset:28672
	ds_read_b128 v[118:121], v174 offset:29696
	ds_read_b128 v[158:161], v174 offset:30720
	ds_read_b128 v[162:165], v174 offset:31744
	s_setprio 1
	s_waitcnt lgkmcnt(0)
	v_mfma_f32_16x16x32_bf16 v[62:65], v[136:139], v[114:117], v[62:65]
	v_mfma_f32_16x16x32_bf16 v[58:61], v[142:145], v[114:117], v[58:61]
	v_mfma_f32_16x16x32_bf16 v[54:57], v[146:149], v[114:117], v[54:57]
	v_mfma_f32_16x16x32_bf16 v[50:53], v[150:153], v[114:117], v[50:53]
	v_mfma_f32_16x16x32_bf16 v[46:49], v[136:139], v[118:121], v[46:49]
	v_mfma_f32_16x16x32_bf16 v[42:45], v[142:145], v[118:121], v[42:45]
	v_mfma_f32_16x16x32_bf16 v[38:41], v[146:149], v[118:121], v[38:41]
	v_mfma_f32_16x16x32_bf16 v[34:37], v[150:153], v[118:121], v[34:37]
	v_mfma_f32_16x16x32_bf16 v[30:33], v[136:139], v[158:161], v[30:33]
	v_mfma_f32_16x16x32_bf16 v[26:29], v[142:145], v[158:161], v[26:29]
	v_mfma_f32_16x16x32_bf16 v[22:25], v[146:149], v[158:161], v[22:25]
	v_mfma_f32_16x16x32_bf16 v[18:21], v[150:153], v[158:161], v[18:21]
	v_mfma_f32_16x16x32_bf16 v[14:17], v[136:139], v[162:165], v[14:17]
	v_mfma_f32_16x16x32_bf16 v[10:13], v[142:145], v[162:165], v[10:13]
	v_mfma_f32_16x16x32_bf16 v[6:9], v[146:149], v[162:165], v[6:9]
	v_mfma_f32_16x16x32_bf16 v[2:5], v[150:153], v[162:165], v[2:5]
	s_setprio 0
	v_lshl_add_u64 v[114:115], s[46:47], 0, v[134:135]
	v_lshl_or_b32 v116, s0, 7, v140
	v_lshlrev_b64 v[120:121], 12, v[114:115]
	v_ashrrev_i32_e32 v117, 31, v116
	v_lshl_add_u64 v[136:137], v[132:133], 0, v[120:121]
	v_lshlrev_b64 v[118:119], 2, v[116:117]
	v_lshl_add_u64 v[146:147], v[136:137], 0, v[118:119]
	s_waitcnt vmcnt(0)
	s_barrier
	v_mov_b32_e32 v212, v146
	v_mov_b32_e32 v213, v147
	global_load_dwordx4 v[180:183], v[212:213], off
	global_load_dwordx4 v[184:187], v[212:213], off offset:64
	global_load_dwordx4 v[188:191], v[212:213], off offset:128
	global_load_dwordx4 v[192:195], v[212:213], off offset:192
	s_mov_b32 s98, 0x10000
	s_mov_b32 s99, 0
	v_lshl_add_u64 v[214:215], v[212:213], 0, s[98:99]
	global_load_dwordx4 v[196:199], v[214:215], off
	global_load_dwordx4 v[200:203], v[214:215], off offset:64
	global_load_dwordx4 v[204:207], v[214:215], off offset:128
	global_load_dwordx4 v[208:211], v[214:215], off offset:192
	v_lshlrev_b64 v[142:143], 11, v[114:115]
	v_lshl_add_u64 v[120:121], v[130:131], 0, v[120:121]
	v_lshl_add_u64 v[142:143], s[8:9], 0, v[142:143]
	v_lshl_add_u64 v[150:151], v[120:121], 0, v[118:119]
	v_lshl_add_u64 v[152:153], v[116:117], 1, v[142:143]
	s_waitcnt vmcnt(4) lgkmcnt(0)
	v_mov_b32_e32 v136, v180
	v_mov_b32_e32 v137, v181
	v_mov_b32_e32 v138, v182
	v_mov_b32_e32 v139, v183
	v_pk_add_f32 v[126:127], v[126:127], v[136:137]
	v_pk_add_f32 v[128:129], v[128:129], v[138:139]
	v_cvt_pk_bf16_f32 v120, v126, v127
	v_cvt_pk_bf16_f32 v121, v128, v129
	global_store_dwordx4 v[150:151], v[126:129], off
	v_mov_b32_e32 v220, v120
	v_mov_b32_e32 v221, v121
	s_nop 0
	s_waitcnt lgkmcnt(0)
	v_mov_b32_e32 v136, v184
	v_mov_b32_e32 v137, v185
	v_mov_b32_e32 v138, v186
	v_mov_b32_e32 v139, v187
	v_pk_add_f32 v[136:137], v[122:123], v[136:137]
	v_pk_add_f32 v[138:139], v[124:125], v[138:139]
	v_cvt_pk_bf16_f32 v120, v136, v137
	v_cvt_pk_bf16_f32 v121, v138, v139
	global_store_dwordx4 v[150:151], v[136:139], off offset:64
	v_mov_b32_e32 v222, v120
	v_mov_b32_e32 v223, v121
	v_mbcnt_lo_u32_b32 v230, -1, 0
	v_mbcnt_hi_u32_b32 v230, -1, v230
	v_and_b32_e32 v230, 16, v230
	v_lshrrev_b32_e32 v228, 1, v230
	v_add_u32_e32 v230, v230, v228
	v_mov_b32_e32 v231, 0
	v_lshl_add_u64 v[228:229], v[152:153], 0, v[230:231]
	v_permlane16_swap_b32_e32 v220, v222
	v_permlane16_swap_b32_e32 v221, v223
	global_store_dwordx4 v[228:229], v[220:223], off
	s_nop 0
	v_pk_mul_f32 v[124:125], v[128:129], v[128:129]
	s_waitcnt lgkmcnt(0)
	v_mov_b32_e32 v120, v188
	v_mov_b32_e32 v121, v189
	v_mov_b32_e32 v122, v190
	v_mov_b32_e32 v123, v191
	v_pk_add_f32 v[142:143], v[170:171], v[120:121]
	v_pk_add_f32 v[144:145], v[172:173], v[122:123]
	v_cvt_pk_bf16_f32 v120, v142, v143
	v_cvt_pk_bf16_f32 v121, v144, v145
	global_store_dwordx4 v[150:151], v[142:145], off offset:128
	v_mov_b32_e32 v224, v120
	v_mov_b32_e32 v225, v121
	s_nop 0
	v_and_b32_e32 v121, 64, v141
	v_xor_b32_e32 v120, 16, v141
	v_add_u32_e32 v123, 64, v121
	v_cmp_lt_i32_e64 s[0:1], v120, v123
	s_nop 1
	v_cndmask_b32_e64 v120, v141, v120, s[0:1]
	v_lshlrev_b32_e32 v122, 2, v120
	v_pk_mul_f32 v[120:121], v[126:127], v[126:127]
	s_nop 0
	v_add_f32_e32 v120, v120, v121
	v_add_f32_e32 v120, v120, v124
	v_add_f32_e32 v126, v120, v125
	v_pk_mul_f32 v[120:121], v[136:137], v[136:137]
	v_pk_mul_f32 v[124:125], v[138:139], v[138:139]
	v_add_f32_e32 v120, v120, v121
	v_add_f32_e32 v120, v120, v124
	v_add_f32_e32 v120, v120, v125
	v_add_f32_e32 v136, v126, v120
	v_pk_mul_f32 v[120:121], v[142:143], v[142:143]
	v_pk_mul_f32 v[124:125], v[144:145], v[144:145]
	v_add_f32_e32 v120, v120, v121
	v_add_f32_e32 v120, v120, v124
	v_add_f32_e32 v137, v120, v125
	v_add_f32_e32 v136, v136, v137
	s_waitcnt lgkmcnt(0)
	v_mov_b32_e32 v146, v192
	v_mov_b32_e32 v147, v193
	v_mov_b32_e32 v148, v194
	v_mov_b32_e32 v149, v195
	v_pk_add_f32 v[124:125], v[154:155], v[146:147]
	v_pk_add_f32 v[126:127], v[156:157], v[148:149]
	v_pk_mul_f32 v[120:121], v[124:125], v[124:125]
	v_pk_mul_f32 v[128:129], v[126:127], v[126:127]
	v_add_f32_e32 v120, v120, v121
	v_add_f32_e32 v120, v120, v128
	v_add_f32_e32 v120, v120, v129
	v_add_f32_e32 v120, v136, v120
	ds_bpermute_b32 v121, v122, v120
	v_xor_b32_e32 v128, 32, v141
	v_cmp_lt_i32_e64 s[0:1], v128, v123
	global_store_dwordx4 v[150:151], v[124:127], off offset:192
	s_waitcnt lgkmcnt(0)
	v_add_f32_e32 v120, v120, v121
	v_cndmask_b32_e64 v123, v141, v128, s[0:1]
	v_lshlrev_b32_e32 v123, 2, v123
	ds_bpermute_b32 v121, v123, v120
	v_cvt_pk_bf16_f32 v124, v124, v125
	v_cvt_pk_bf16_f32 v125, v126, v127
	v_mov_b32_e32 v226, v124
	v_mov_b32_e32 v227, v125
	s_nop 1
	v_lshl_add_u64 v[228:229], v[152:153], 0, v[230:231]
	v_permlane16_swap_b32_e32 v224, v226
	v_permlane16_swap_b32_e32 v225, v227
	global_store_dwordx4 v[228:229], v[224:227], off offset:64
	s_and_saveexec_b64 s[0:1], vcc
	s_cbranch_execz .LBB0_534
	s_waitcnt lgkmcnt(0)
	v_add_f32_e32 v124, v120, v121
	v_lshl_add_u64 v[120:121], v[114:115], 2, s[10:11]
	global_atomic_add_f32 v[120:121], v124, off
.LBB0_534:
	s_or_b64 exec, exec, s[0:1]
	v_or_b32_e32 v120, 16, v114
	s_waitcnt lgkmcnt(0)
	v_mov_b32_e32 v121, v115
	v_lshlrev_b64 v[128:129], 12, v[120:121]
	v_lshl_add_u64 v[124:125], v[132:133], 0, v[128:129]
	v_lshl_add_u64 v[136:137], v[124:125], 0, v[118:119]
	s_mov_b32 s98, 0x20000
	s_mov_b32 s99, 0
	v_lshl_add_u64 v[214:215], v[212:213], 0, s[98:99]
	global_load_dwordx4 v[180:183], v[214:215], off
	global_load_dwordx4 v[184:187], v[214:215], off offset:64
	global_load_dwordx4 v[188:191], v[214:215], off offset:128
	global_load_dwordx4 v[192:195], v[214:215], off offset:192
	v_lshlrev_b64 v[138:139], 11, v[120:121]
	v_lshl_add_u64 v[128:129], v[130:131], 0, v[128:129]
	v_lshl_add_u64 v[138:139], s[8:9], 0, v[138:139]
	v_lshl_add_u64 v[128:129], v[128:129], 0, v[118:119]
	v_lshl_add_u64 v[138:139], v[116:117], 1, v[138:139]
	s_waitcnt vmcnt(10) lgkmcnt(0)
	v_mov_b32_e32 v124, v196
	v_mov_b32_e32 v125, v197
	v_mov_b32_e32 v126, v198
	v_mov_b32_e32 v127, v199
	v_pk_add_f32 v[110:111], v[110:111], v[124:125]
	v_pk_add_f32 v[112:113], v[112:113], v[126:127]
	v_cvt_pk_bf16_f32 v124, v110, v111
	v_cvt_pk_bf16_f32 v125, v112, v113
	global_store_dwordx4 v[128:129], v[110:113], off
	v_mov_b32_e32 v220, v124
	v_mov_b32_e32 v221, v125
	s_nop 0
	v_pk_mul_f32 v[110:111], v[110:111], v[110:111]
	v_pk_mul_f32 v[112:113], v[112:113], v[112:113]
	v_add_f32_e32 v110, v110, v111
	v_add_f32_e32 v110, v110, v112
	v_add_f32_e32 v110, v110, v113
	s_waitcnt lgkmcnt(0)
	v_mov_b32_e32 v124, v200
	v_mov_b32_e32 v125, v201
	v_mov_b32_e32 v126, v202
	v_mov_b32_e32 v127, v203
	v_pk_add_f32 v[106:107], v[106:107], v[124:125]
	v_pk_add_f32 v[108:109], v[108:109], v[126:127]
	v_cvt_pk_bf16_f32 v124, v106, v107
	v_cvt_pk_bf16_f32 v125, v108, v109
	global_store_dwordx4 v[128:129], v[106:109], off offset:64
	v_mov_b32_e32 v222, v124
	v_mov_b32_e32 v223, v125
	v_mbcnt_lo_u32_b32 v230, -1, 0
	v_mbcnt_hi_u32_b32 v230, -1, v230
	v_and_b32_e32 v230, 16, v230
	v_lshrrev_b32_e32 v228, 1, v230
	v_add_u32_e32 v230, v230, v228
	v_mov_b32_e32 v231, 0
	v_lshl_add_u64 v[228:229], v[138:139], 0, v[230:231]
	v_permlane16_swap_b32_e32 v220, v222
	v_permlane16_swap_b32_e32 v221, v223
	global_store_dwordx4 v[228:229], v[220:223], off
	s_nop 0
	v_pk_mul_f32 v[106:107], v[106:107], v[106:107]
	v_pk_mul_f32 v[108:109], v[108:109], v[108:109]
	v_add_f32_e32 v106, v106, v107
	v_add_f32_e32 v106, v106, v108
	v_add_f32_e32 v106, v106, v109
	v_add_f32_e32 v106, v110, v106
	s_waitcnt lgkmcnt(0)
	v_mov_b32_e32 v124, v204
	v_mov_b32_e32 v125, v205
	v_mov_b32_e32 v126, v206
	v_mov_b32_e32 v127, v207
	v_pk_add_f32 v[102:103], v[102:103], v[124:125]
	v_pk_add_f32 v[104:105], v[104:105], v[126:127]
	v_cvt_pk_bf16_f32 v124, v102, v103
	v_cvt_pk_bf16_f32 v125, v104, v105
	global_store_dwordx4 v[128:129], v[102:105], off offset:128
	v_mov_b32_e32 v224, v124
	v_mov_b32_e32 v225, v125
	s_nop 0
	v_pk_mul_f32 v[102:103], v[102:103], v[102:103]
	v_pk_mul_f32 v[104:105], v[104:105], v[104:105]
	v_add_f32_e32 v102, v102, v103
	v_add_f32_e32 v102, v102, v104
	v_add_f32_e32 v107, v102, v105
	v_add_f32_e32 v106, v106, v107
	s_waitcnt lgkmcnt(0)
	v_mov_b32_e32 v124, v208
	v_mov_b32_e32 v125, v209
	v_mov_b32_e32 v126, v210
	v_mov_b32_e32 v127, v211
	v_pk_add_f32 v[102:103], v[98:99], v[124:125]
	v_pk_add_f32 v[104:105], v[100:101], v[126:127]
	v_pk_mul_f32 v[98:99], v[102:103], v[102:103]
	v_pk_mul_f32 v[100:101], v[104:105], v[104:105]
	v_add_f32_e32 v98, v98, v99
	v_add_f32_e32 v98, v98, v100
	v_add_f32_e32 v98, v98, v101
	v_add_f32_e32 v98, v106, v98
	ds_bpermute_b32 v99, v122, v98
	v_cvt_pk_bf16_f32 v100, v102, v103
	v_cvt_pk_bf16_f32 v101, v104, v105
	global_store_dwordx4 v[128:129], v[102:105], off offset:192
	v_mov_b32_e32 v226, v100
	v_mov_b32_e32 v227, v101
	s_nop 1
	v_lshl_add_u64 v[228:229], v[138:139], 0, v[230:231]
	v_permlane16_swap_b32_e32 v224, v226
	v_permlane16_swap_b32_e32 v225, v227
	global_store_dwordx4 v[228:229], v[224:227], off offset:64
	s_waitcnt lgkmcnt(0)
	v_add_f32_e32 v98, v98, v99
	ds_bpermute_b32 v99, v123, v98
	s_and_saveexec_b64 s[0:1], vcc
	s_cbranch_execz .LBB0_536
	s_waitcnt lgkmcnt(0)
	v_add_f32_e32 v100, v98, v99
	v_lshl_add_u64 v[98:99], v[120:121], 2, s[10:11]
	global_atomic_add_f32 v[98:99], v100, off
.LBB0_536:
	s_or_b64 exec, exec, s[0:1]
	v_or_b32_e32 v98, 32, v114
	s_waitcnt lgkmcnt(0)
	v_mov_b32_e32 v99, v115
	v_lshlrev_b64 v[104:105], 12, v[98:99]
	v_lshl_add_u64 v[100:101], v[132:133], 0, v[104:105]
	v_lshl_add_u64 v[106:107], v[100:101], 0, v[118:119]
	s_mov_b32 s98, 0x30000
	s_mov_b32 s99, 0
	v_lshl_add_u64 v[214:215], v[212:213], 0, s[98:99]
	global_load_dwordx4 v[196:199], v[214:215], off
	global_load_dwordx4 v[200:203], v[214:215], off offset:64
	global_load_dwordx4 v[204:207], v[214:215], off offset:128
	global_load_dwordx4 v[208:211], v[214:215], off offset:192
	v_lshlrev_b64 v[108:109], 11, v[98:99]
	v_lshl_add_u64 v[104:105], v[130:131], 0, v[104:105]
	v_lshl_add_u64 v[108:109], s[8:9], 0, v[108:109]
	v_lshl_add_u64 v[104:105], v[104:105], 0, v[118:119]
	v_lshl_add_u64 v[108:109], v[116:117], 1, v[108:109]
	s_waitcnt vmcnt(10) lgkmcnt(0)
	v_mov_b32_e32 v100, v180
	v_mov_b32_e32 v101, v181
	v_mov_b32_e32 v102, v182
	v_mov_b32_e32 v103, v183
	v_pk_add_f32 v[94:95], v[94:95], v[100:101]
	v_pk_add_f32 v[96:97], v[96:97], v[102:103]
	v_cvt_pk_bf16_f32 v100, v94, v95
	v_cvt_pk_bf16_f32 v101, v96, v97
	global_store_dwordx4 v[104:105], v[94:97], off
	v_mov_b32_e32 v220, v100
	v_mov_b32_e32 v221, v101
	s_nop 0
	v_pk_mul_f32 v[94:95], v[94:95], v[94:95]
	v_pk_mul_f32 v[96:97], v[96:97], v[96:97]
	v_add_f32_e32 v94, v94, v95
	v_add_f32_e32 v94, v94, v96
	v_add_f32_e32 v94, v94, v97
	s_waitcnt lgkmcnt(0)
	v_mov_b32_e32 v100, v184
	v_mov_b32_e32 v101, v185
	v_mov_b32_e32 v102, v186
	v_mov_b32_e32 v103, v187
	v_pk_add_f32 v[90:91], v[90:91], v[100:101]
	v_pk_add_f32 v[92:93], v[92:93], v[102:103]
	v_cvt_pk_bf16_f32 v100, v90, v91
	v_cvt_pk_bf16_f32 v101, v92, v93
	global_store_dwordx4 v[104:105], v[90:93], off offset:64
	v_mov_b32_e32 v222, v100
	v_mov_b32_e32 v223, v101
	v_mbcnt_lo_u32_b32 v230, -1, 0
	v_mbcnt_hi_u32_b32 v230, -1, v230
	v_and_b32_e32 v230, 16, v230
	v_lshrrev_b32_e32 v228, 1, v230
	v_add_u32_e32 v230, v230, v228
	v_mov_b32_e32 v231, 0
	v_lshl_add_u64 v[228:229], v[108:109], 0, v[230:231]
	v_permlane16_swap_b32_e32 v220, v222
	v_permlane16_swap_b32_e32 v221, v223
	global_store_dwordx4 v[228:229], v[220:223], off
	s_nop 0
	v_pk_mul_f32 v[90:91], v[90:91], v[90:91]
	v_pk_mul_f32 v[92:93], v[92:93], v[92:93]
	v_add_f32_e32 v90, v90, v91
	v_add_f32_e32 v90, v90, v92
	v_add_f32_e32 v90, v90, v93
	v_add_f32_e32 v90, v94, v90
	s_waitcnt lgkmcnt(0)
	v_mov_b32_e32 v100, v188
	v_mov_b32_e32 v101, v189
	v_mov_b32_e32 v102, v190
	v_mov_b32_e32 v103, v191
	v_pk_add_f32 v[86:87], v[86:87], v[100:101]
	v_pk_add_f32 v[88:89], v[88:89], v[102:103]
	v_cvt_pk_bf16_f32 v100, v86, v87
	v_cvt_pk_bf16_f32 v101, v88, v89
	global_store_dwordx4 v[104:105], v[86:89], off offset:128
	v_mov_b32_e32 v224, v100
	v_mov_b32_e32 v225, v101
	s_nop 0
	v_pk_mul_f32 v[86:87], v[86:87], v[86:87]
	v_pk_mul_f32 v[88:89], v[88:89], v[88:89]
	v_add_f32_e32 v86, v86, v87
	v_add_f32_e32 v86, v86, v88
	v_add_f32_e32 v91, v86, v89
	v_add_f32_e32 v90, v90, v91
	s_waitcnt lgkmcnt(0)
	v_mov_b32_e32 v100, v192
	v_mov_b32_e32 v101, v193
	v_mov_b32_e32 v102, v194
	v_mov_b32_e32 v103, v195
	v_pk_add_f32 v[86:87], v[82:83], v[100:101]
	v_pk_add_f32 v[88:89], v[84:85], v[102:103]
	v_pk_mul_f32 v[82:83], v[86:87], v[86:87]
	v_pk_mul_f32 v[84:85], v[88:89], v[88:89]
	v_add_f32_e32 v82, v82, v83
	v_add_f32_e32 v82, v82, v84
	v_add_f32_e32 v82, v82, v85
	v_add_f32_e32 v82, v90, v82
	ds_bpermute_b32 v83, v122, v82
	v_cvt_pk_bf16_f32 v84, v86, v87
	v_cvt_pk_bf16_f32 v85, v88, v89
	global_store_dwordx4 v[104:105], v[86:89], off offset:192
	v_mov_b32_e32 v226, v84
	v_mov_b32_e32 v227, v85
	s_nop 1
	v_lshl_add_u64 v[228:229], v[108:109], 0, v[230:231]
	v_permlane16_swap_b32_e32 v224, v226
	v_permlane16_swap_b32_e32 v225, v227
	global_store_dwordx4 v[228:229], v[224:227], off offset:64
	s_waitcnt lgkmcnt(0)
	v_add_f32_e32 v82, v82, v83
	ds_bpermute_b32 v83, v123, v82
	s_and_saveexec_b64 s[0:1], vcc
	s_cbranch_execz .LBB0_538
	s_waitcnt lgkmcnt(0)
	v_add_f32_e32 v84, v82, v83
	v_lshl_add_u64 v[82:83], v[98:99], 2, s[10:11]
	global_atomic_add_f32 v[82:83], v84, off
.LBB0_538:
	s_or_b64 exec, exec, s[0:1]
	v_or_b32_e32 v82, 48, v114
	s_waitcnt lgkmcnt(0)
	v_mov_b32_e32 v83, v115
	v_lshlrev_b64 v[88:89], 12, v[82:83]
	v_lshl_add_u64 v[84:85], v[132:133], 0, v[88:89]
	v_lshl_add_u64 v[90:91], v[84:85], 0, v[118:119]
	s_mov_b32 s98, 0x40000
	s_mov_b32 s99, 0
	v_lshl_add_u64 v[214:215], v[212:213], 0, s[98:99]
	global_load_dwordx4 v[180:183], v[214:215], off
	global_load_dwordx4 v[184:187], v[214:215], off offset:64
	global_load_dwordx4 v[188:191], v[214:215], off offset:128
	global_load_dwordx4 v[192:195], v[214:215], off offset:192
	v_lshlrev_b64 v[92:93], 11, v[82:83]
	v_lshl_add_u64 v[88:89], v[130:131], 0, v[88:89]
	v_lshl_add_u64 v[92:93], s[8:9], 0, v[92:93]
	v_lshl_add_u64 v[88:89], v[88:89], 0, v[118:119]
	v_lshl_add_u64 v[92:93], v[116:117], 1, v[92:93]
	s_waitcnt vmcnt(10) lgkmcnt(0)
	v_mov_b32_e32 v84, v196
	v_mov_b32_e32 v85, v197
	v_mov_b32_e32 v86, v198
	v_mov_b32_e32 v87, v199
	v_pk_add_f32 v[78:79], v[78:79], v[84:85]
	v_pk_add_f32 v[80:81], v[80:81], v[86:87]
	v_cvt_pk_bf16_f32 v84, v78, v79
	v_cvt_pk_bf16_f32 v85, v80, v81
	global_store_dwordx4 v[88:89], v[78:81], off
	v_mov_b32_e32 v220, v84
	v_mov_b32_e32 v221, v85
	s_nop 0
	v_pk_mul_f32 v[78:79], v[78:79], v[78:79]
	v_pk_mul_f32 v[80:81], v[80:81], v[80:81]
	v_add_f32_e32 v78, v78, v79
	v_add_f32_e32 v78, v78, v80
	v_add_f32_e32 v78, v78, v81
	s_waitcnt lgkmcnt(0)
	v_mov_b32_e32 v84, v200
	v_mov_b32_e32 v85, v201
	v_mov_b32_e32 v86, v202
	v_mov_b32_e32 v87, v203
	v_pk_add_f32 v[74:75], v[74:75], v[84:85]
	v_pk_add_f32 v[76:77], v[76:77], v[86:87]
	v_cvt_pk_bf16_f32 v84, v74, v75
	v_cvt_pk_bf16_f32 v85, v76, v77
	global_store_dwordx4 v[88:89], v[74:77], off offset:64
	v_mov_b32_e32 v222, v84
	v_mov_b32_e32 v223, v85
	v_mbcnt_lo_u32_b32 v230, -1, 0
	v_mbcnt_hi_u32_b32 v230, -1, v230
	v_and_b32_e32 v230, 16, v230
	v_lshrrev_b32_e32 v228, 1, v230
	v_add_u32_e32 v230, v230, v228
	v_mov_b32_e32 v231, 0
	v_lshl_add_u64 v[228:229], v[92:93], 0, v[230:231]
	v_permlane16_swap_b32_e32 v220, v222
	v_permlane16_swap_b32_e32 v221, v223
	global_store_dwordx4 v[228:229], v[220:223], off
	s_nop 0
	v_pk_mul_f32 v[74:75], v[74:75], v[74:75]
	v_pk_mul_f32 v[76:77], v[76:77], v[76:77]
	v_add_f32_e32 v74, v74, v75
	v_add_f32_e32 v74, v74, v76
	v_add_f32_e32 v74, v74, v77
	v_add_f32_e32 v74, v78, v74
	s_waitcnt lgkmcnt(0)
	v_mov_b32_e32 v84, v204
	v_mov_b32_e32 v85, v205
	v_mov_b32_e32 v86, v206
	v_mov_b32_e32 v87, v207
	v_pk_add_f32 v[70:71], v[70:71], v[84:85]
	v_pk_add_f32 v[72:73], v[72:73], v[86:87]
	v_cvt_pk_bf16_f32 v84, v70, v71
	v_cvt_pk_bf16_f32 v85, v72, v73
	global_store_dwordx4 v[88:89], v[70:73], off offset:128
	v_mov_b32_e32 v224, v84
	v_mov_b32_e32 v225, v85
	s_nop 0
	v_pk_mul_f32 v[70:71], v[70:71], v[70:71]
	v_pk_mul_f32 v[72:73], v[72:73], v[72:73]
	v_add_f32_e32 v70, v70, v71
	v_add_f32_e32 v70, v70, v72
	v_add_f32_e32 v75, v70, v73
	v_add_f32_e32 v74, v74, v75
	s_waitcnt lgkmcnt(0)
	v_mov_b32_e32 v84, v208
	v_mov_b32_e32 v85, v209
	v_mov_b32_e32 v86, v210
	v_mov_b32_e32 v87, v211
	v_pk_add_f32 v[70:71], v[66:67], v[84:85]
	v_pk_add_f32 v[72:73], v[68:69], v[86:87]
	v_pk_mul_f32 v[66:67], v[70:71], v[70:71]
	v_pk_mul_f32 v[68:69], v[72:73], v[72:73]
	v_add_f32_e32 v66, v66, v67
	v_add_f32_e32 v66, v66, v68
	v_add_f32_e32 v66, v66, v69
	v_add_f32_e32 v66, v74, v66
	ds_bpermute_b32 v67, v122, v66
	v_cvt_pk_bf16_f32 v68, v70, v71
	v_cvt_pk_bf16_f32 v69, v72, v73
	global_store_dwordx4 v[88:89], v[70:73], off offset:192
	v_mov_b32_e32 v226, v68
	v_mov_b32_e32 v227, v69
	s_nop 1
	v_lshl_add_u64 v[228:229], v[92:93], 0, v[230:231]
	v_permlane16_swap_b32_e32 v224, v226
	v_permlane16_swap_b32_e32 v225, v227
	global_store_dwordx4 v[228:229], v[224:227], off offset:64
	s_waitcnt lgkmcnt(0)
	v_add_f32_e32 v66, v66, v67
	ds_bpermute_b32 v67, v123, v66
	s_and_saveexec_b64 s[0:1], vcc
	s_cbranch_execz .LBB0_540
	s_waitcnt lgkmcnt(0)
	v_add_f32_e32 v68, v66, v67
	v_lshl_add_u64 v[66:67], v[82:83], 2, s[10:11]
	global_atomic_add_f32 v[66:67], v68, off
.LBB0_540:
	s_or_b64 exec, exec, s[0:1]
	v_or_b32_e32 v66, 64, v114
	s_waitcnt lgkmcnt(0)
	v_mov_b32_e32 v67, v115
	v_lshlrev_b64 v[72:73], 12, v[66:67]
	v_lshl_add_u64 v[68:69], v[132:133], 0, v[72:73]
	v_lshl_add_u64 v[74:75], v[68:69], 0, v[118:119]
	s_mov_b32 s98, 0x50000
	s_mov_b32 s99, 0
	v_lshl_add_u64 v[214:215], v[212:213], 0, s[98:99]
	global_load_dwordx4 v[196:199], v[214:215], off
	global_load_dwordx4 v[200:203], v[214:215], off offset:64
	global_load_dwordx4 v[204:207], v[214:215], off offset:128
	global_load_dwordx4 v[208:211], v[214:215], off offset:192
	v_lshlrev_b64 v[76:77], 11, v[66:67]
	v_lshl_add_u64 v[72:73], v[130:131], 0, v[72:73]
	v_lshl_add_u64 v[76:77], s[8:9], 0, v[76:77]
	v_lshl_add_u64 v[72:73], v[72:73], 0, v[118:119]
	v_lshl_add_u64 v[76:77], v[116:117], 1, v[76:77]
	s_waitcnt vmcnt(10) lgkmcnt(0)
	v_mov_b32_e32 v68, v180
	v_mov_b32_e32 v69, v181
	v_mov_b32_e32 v70, v182
	v_mov_b32_e32 v71, v183
	v_pk_add_f32 v[62:63], v[62:63], v[68:69]
	v_pk_add_f32 v[64:65], v[64:65], v[70:71]
	v_cvt_pk_bf16_f32 v68, v62, v63
	v_cvt_pk_bf16_f32 v69, v64, v65
	global_store_dwordx4 v[72:73], v[62:65], off
	v_mov_b32_e32 v220, v68
	v_mov_b32_e32 v221, v69
	s_nop 0
	v_pk_mul_f32 v[62:63], v[62:63], v[62:63]
	v_pk_mul_f32 v[64:65], v[64:65], v[64:65]
	v_add_f32_e32 v62, v62, v63
	v_add_f32_e32 v62, v62, v64
	v_add_f32_e32 v62, v62, v65
	s_waitcnt lgkmcnt(0)
	v_mov_b32_e32 v68, v184
	v_mov_b32_e32 v69, v185
	v_mov_b32_e32 v70, v186
	v_mov_b32_e32 v71, v187
	v_pk_add_f32 v[58:59], v[58:59], v[68:69]
	v_pk_add_f32 v[60:61], v[60:61], v[70:71]
	v_cvt_pk_bf16_f32 v68, v58, v59
	v_cvt_pk_bf16_f32 v69, v60, v61
	global_store_dwordx4 v[72:73], v[58:61], off offset:64
	v_mov_b32_e32 v222, v68
	v_mov_b32_e32 v223, v69
	v_mbcnt_lo_u32_b32 v230, -1, 0
	v_mbcnt_hi_u32_b32 v230, -1, v230
	v_and_b32_e32 v230, 16, v230
	v_lshrrev_b32_e32 v228, 1, v230
	v_add_u32_e32 v230, v230, v228
	v_mov_b32_e32 v231, 0
	v_lshl_add_u64 v[228:229], v[76:77], 0, v[230:231]
	v_permlane16_swap_b32_e32 v220, v222
	v_permlane16_swap_b32_e32 v221, v223
	global_store_dwordx4 v[228:229], v[220:223], off
	s_nop 0
	v_pk_mul_f32 v[58:59], v[58:59], v[58:59]
	v_pk_mul_f32 v[60:61], v[60:61], v[60:61]
	v_add_f32_e32 v58, v58, v59
	v_add_f32_e32 v58, v58, v60
	v_add_f32_e32 v58, v58, v61
	v_add_f32_e32 v58, v62, v58
	s_waitcnt lgkmcnt(0)
	v_mov_b32_e32 v68, v188
	v_mov_b32_e32 v69, v189
	v_mov_b32_e32 v70, v190
	v_mov_b32_e32 v71, v191
	v_pk_add_f32 v[54:55], v[54:55], v[68:69]
	v_pk_add_f32 v[56:57], v[56:57], v[70:71]
	v_cvt_pk_bf16_f32 v68, v54, v55
	v_cvt_pk_bf16_f32 v69, v56, v57
	global_store_dwordx4 v[72:73], v[54:57], off offset:128
	v_mov_b32_e32 v224, v68
	v_mov_b32_e32 v225, v69
	s_nop 0
	v_pk_mul_f32 v[54:55], v[54:55], v[54:55]
	v_pk_mul_f32 v[56:57], v[56:57], v[56:57]
	v_add_f32_e32 v54, v54, v55
	v_add_f32_e32 v54, v54, v56
	v_add_f32_e32 v59, v54, v57
	v_add_f32_e32 v58, v58, v59
	s_waitcnt lgkmcnt(0)
	v_mov_b32_e32 v68, v192
	v_mov_b32_e32 v69, v193
	v_mov_b32_e32 v70, v194
	v_mov_b32_e32 v71, v195
	v_pk_add_f32 v[54:55], v[50:51], v[68:69]
	v_pk_add_f32 v[56:57], v[52:53], v[70:71]
	v_pk_mul_f32 v[50:51], v[54:55], v[54:55]
	v_pk_mul_f32 v[52:53], v[56:57], v[56:57]
	v_add_f32_e32 v50, v50, v51
	v_add_f32_e32 v50, v50, v52
	v_add_f32_e32 v50, v50, v53
	v_add_f32_e32 v50, v58, v50
	ds_bpermute_b32 v51, v122, v50
	v_cvt_pk_bf16_f32 v52, v54, v55
	v_cvt_pk_bf16_f32 v53, v56, v57
	global_store_dwordx4 v[72:73], v[54:57], off offset:192
	v_mov_b32_e32 v226, v52
	v_mov_b32_e32 v227, v53
	s_nop 1
	v_lshl_add_u64 v[228:229], v[76:77], 0, v[230:231]
	v_permlane16_swap_b32_e32 v224, v226
	v_permlane16_swap_b32_e32 v225, v227
	global_store_dwordx4 v[228:229], v[224:227], off offset:64
	s_waitcnt lgkmcnt(0)
	v_add_f32_e32 v50, v50, v51
	ds_bpermute_b32 v51, v123, v50
	s_and_saveexec_b64 s[0:1], vcc
	s_cbranch_execz .LBB0_542
	s_waitcnt lgkmcnt(0)
	v_add_f32_e32 v52, v50, v51
	v_lshl_add_u64 v[50:51], v[66:67], 2, s[10:11]
	global_atomic_add_f32 v[50:51], v52, off
.LBB0_542:
	s_or_b64 exec, exec, s[0:1]
	v_or_b32_e32 v50, 0x50, v114
	s_waitcnt lgkmcnt(0)
	v_mov_b32_e32 v51, v115
	v_lshlrev_b64 v[56:57], 12, v[50:51]
	v_lshl_add_u64 v[52:53], v[132:133], 0, v[56:57]
	v_lshl_add_u64 v[58:59], v[52:53], 0, v[118:119]
	s_mov_b32 s98, 0x60000
	s_mov_b32 s99, 0
	v_lshl_add_u64 v[214:215], v[212:213], 0, s[98:99]
	global_load_dwordx4 v[180:183], v[214:215], off
	global_load_dwordx4 v[184:187], v[214:215], off offset:64
	global_load_dwordx4 v[188:191], v[214:215], off offset:128
	global_load_dwordx4 v[192:195], v[214:215], off offset:192
	v_lshlrev_b64 v[60:61], 11, v[50:51]
	v_lshl_add_u64 v[56:57], v[130:131], 0, v[56:57]
	v_lshl_add_u64 v[60:61], s[8:9], 0, v[60:61]
	v_lshl_add_u64 v[56:57], v[56:57], 0, v[118:119]
	v_lshl_add_u64 v[60:61], v[116:117], 1, v[60:61]
	s_waitcnt vmcnt(10) lgkmcnt(0)
	v_mov_b32_e32 v52, v196
	v_mov_b32_e32 v53, v197
	v_mov_b32_e32 v54, v198
	v_mov_b32_e32 v55, v199
	v_pk_add_f32 v[46:47], v[46:47], v[52:53]
	v_pk_add_f32 v[48:49], v[48:49], v[54:55]
	v_cvt_pk_bf16_f32 v52, v46, v47
	v_cvt_pk_bf16_f32 v53, v48, v49
	global_store_dwordx4 v[56:57], v[46:49], off
	v_mov_b32_e32 v220, v52
	v_mov_b32_e32 v221, v53
	s_nop 0
	v_pk_mul_f32 v[46:47], v[46:47], v[46:47]
	v_pk_mul_f32 v[48:49], v[48:49], v[48:49]
	v_add_f32_e32 v46, v46, v47
	v_add_f32_e32 v46, v46, v48
	v_add_f32_e32 v46, v46, v49
	s_waitcnt lgkmcnt(0)
	v_mov_b32_e32 v52, v200
	v_mov_b32_e32 v53, v201
	v_mov_b32_e32 v54, v202
	v_mov_b32_e32 v55, v203
	v_pk_add_f32 v[42:43], v[42:43], v[52:53]
	v_pk_add_f32 v[44:45], v[44:45], v[54:55]
	v_cvt_pk_bf16_f32 v52, v42, v43
	v_cvt_pk_bf16_f32 v53, v44, v45
	global_store_dwordx4 v[56:57], v[42:45], off offset:64
	v_mov_b32_e32 v222, v52
	v_mov_b32_e32 v223, v53
	v_mbcnt_lo_u32_b32 v230, -1, 0
	v_mbcnt_hi_u32_b32 v230, -1, v230
	v_and_b32_e32 v230, 16, v230
	v_lshrrev_b32_e32 v228, 1, v230
	v_add_u32_e32 v230, v230, v228
	v_mov_b32_e32 v231, 0
	v_lshl_add_u64 v[228:229], v[60:61], 0, v[230:231]
	v_permlane16_swap_b32_e32 v220, v222
	v_permlane16_swap_b32_e32 v221, v223
	global_store_dwordx4 v[228:229], v[220:223], off
	s_nop 0
	v_pk_mul_f32 v[42:43], v[42:43], v[42:43]
	v_pk_mul_f32 v[44:45], v[44:45], v[44:45]
	v_add_f32_e32 v42, v42, v43
	v_add_f32_e32 v42, v42, v44
	v_add_f32_e32 v42, v42, v45
	v_add_f32_e32 v42, v46, v42
	s_waitcnt lgkmcnt(0)
	v_mov_b32_e32 v52, v204
	v_mov_b32_e32 v53, v205
	v_mov_b32_e32 v54, v206
	v_mov_b32_e32 v55, v207
	v_pk_add_f32 v[38:39], v[38:39], v[52:53]
	v_pk_add_f32 v[40:41], v[40:41], v[54:55]
	v_cvt_pk_bf16_f32 v52, v38, v39
	v_cvt_pk_bf16_f32 v53, v40, v41
	global_store_dwordx4 v[56:57], v[38:41], off offset:128
	v_mov_b32_e32 v224, v52
	v_mov_b32_e32 v225, v53
	s_nop 0
	v_pk_mul_f32 v[38:39], v[38:39], v[38:39]
	v_pk_mul_f32 v[40:41], v[40:41], v[40:41]
	v_add_f32_e32 v38, v38, v39
	v_add_f32_e32 v38, v38, v40
	v_add_f32_e32 v43, v38, v41
	v_add_f32_e32 v42, v42, v43
	s_waitcnt lgkmcnt(0)
	v_mov_b32_e32 v52, v208
	v_mov_b32_e32 v53, v209
	v_mov_b32_e32 v54, v210
	v_mov_b32_e32 v55, v211
	v_pk_add_f32 v[38:39], v[34:35], v[52:53]
	v_pk_add_f32 v[40:41], v[36:37], v[54:55]
	v_pk_mul_f32 v[34:35], v[38:39], v[38:39]
	v_pk_mul_f32 v[36:37], v[40:41], v[40:41]
	v_add_f32_e32 v34, v34, v35
	v_add_f32_e32 v34, v34, v36
	v_add_f32_e32 v34, v34, v37
	v_add_f32_e32 v34, v42, v34
	ds_bpermute_b32 v35, v122, v34
	v_cvt_pk_bf16_f32 v36, v38, v39
	v_cvt_pk_bf16_f32 v37, v40, v41
	global_store_dwordx4 v[56:57], v[38:41], off offset:192
	v_mov_b32_e32 v226, v36
	v_mov_b32_e32 v227, v37
	s_nop 1
	v_lshl_add_u64 v[228:229], v[60:61], 0, v[230:231]
	v_permlane16_swap_b32_e32 v224, v226
	v_permlane16_swap_b32_e32 v225, v227
	global_store_dwordx4 v[228:229], v[224:227], off offset:64
	s_waitcnt lgkmcnt(0)
	v_add_f32_e32 v34, v34, v35
	ds_bpermute_b32 v35, v123, v34
	s_and_saveexec_b64 s[0:1], vcc
	s_cbranch_execz .LBB0_544
	s_waitcnt lgkmcnt(0)
	v_add_f32_e32 v36, v34, v35
	v_lshl_add_u64 v[34:35], v[50:51], 2, s[10:11]
	global_atomic_add_f32 v[34:35], v36, off
.LBB0_544:
	s_or_b64 exec, exec, s[0:1]
	v_or_b32_e32 v34, 0x60, v114
	s_waitcnt lgkmcnt(0)
	v_mov_b32_e32 v35, v115
	v_lshlrev_b64 v[40:41], 12, v[34:35]
	v_lshl_add_u64 v[36:37], v[132:133], 0, v[40:41]
	v_lshl_add_u64 v[42:43], v[36:37], 0, v[118:119]
	s_mov_b32 s98, 0x70000
	s_mov_b32 s99, 0
	v_lshl_add_u64 v[214:215], v[212:213], 0, s[98:99]
	global_load_dwordx4 v[196:199], v[214:215], off
	global_load_dwordx4 v[200:203], v[214:215], off offset:64
	global_load_dwordx4 v[204:207], v[214:215], off offset:128
	global_load_dwordx4 v[208:211], v[214:215], off offset:192
	v_lshlrev_b64 v[44:45], 11, v[34:35]
	v_lshl_add_u64 v[40:41], v[130:131], 0, v[40:41]
	v_lshl_add_u64 v[44:45], s[8:9], 0, v[44:45]
	v_lshl_add_u64 v[40:41], v[40:41], 0, v[118:119]
	v_lshl_add_u64 v[44:45], v[116:117], 1, v[44:45]
	s_waitcnt vmcnt(10) lgkmcnt(0)
	v_mov_b32_e32 v36, v180
	v_mov_b32_e32 v37, v181
	v_mov_b32_e32 v38, v182
	v_mov_b32_e32 v39, v183
	v_pk_add_f32 v[30:31], v[30:31], v[36:37]
	v_pk_add_f32 v[32:33], v[32:33], v[38:39]
	v_cvt_pk_bf16_f32 v36, v30, v31
	v_cvt_pk_bf16_f32 v37, v32, v33
	global_store_dwordx4 v[40:41], v[30:33], off
	v_mov_b32_e32 v220, v36
	v_mov_b32_e32 v221, v37
	s_nop 0
	v_pk_mul_f32 v[30:31], v[30:31], v[30:31]
	v_pk_mul_f32 v[32:33], v[32:33], v[32:33]
	v_add_f32_e32 v30, v30, v31
	v_add_f32_e32 v30, v30, v32
	v_add_f32_e32 v30, v30, v33
	s_waitcnt lgkmcnt(0)
	v_mov_b32_e32 v36, v184
	v_mov_b32_e32 v37, v185
	v_mov_b32_e32 v38, v186
	v_mov_b32_e32 v39, v187
	v_pk_add_f32 v[26:27], v[26:27], v[36:37]
	v_pk_add_f32 v[28:29], v[28:29], v[38:39]
	v_cvt_pk_bf16_f32 v36, v26, v27
	v_cvt_pk_bf16_f32 v37, v28, v29
	global_store_dwordx4 v[40:41], v[26:29], off offset:64
	v_mov_b32_e32 v222, v36
	v_mov_b32_e32 v223, v37
	v_mbcnt_lo_u32_b32 v230, -1, 0
	v_mbcnt_hi_u32_b32 v230, -1, v230
	v_and_b32_e32 v230, 16, v230
	v_lshrrev_b32_e32 v228, 1, v230
	v_add_u32_e32 v230, v230, v228
	v_mov_b32_e32 v231, 0
	v_lshl_add_u64 v[228:229], v[44:45], 0, v[230:231]
	v_permlane16_swap_b32_e32 v220, v222
	v_permlane16_swap_b32_e32 v221, v223
	global_store_dwordx4 v[228:229], v[220:223], off
	s_nop 0
	v_pk_mul_f32 v[26:27], v[26:27], v[26:27]
	v_pk_mul_f32 v[28:29], v[28:29], v[28:29]
	v_add_f32_e32 v26, v26, v27
	v_add_f32_e32 v26, v26, v28
	v_add_f32_e32 v26, v26, v29
	v_add_f32_e32 v26, v30, v26
	s_waitcnt lgkmcnt(0)
	v_mov_b32_e32 v36, v188
	v_mov_b32_e32 v37, v189
	v_mov_b32_e32 v38, v190
	v_mov_b32_e32 v39, v191
	v_pk_add_f32 v[22:23], v[22:23], v[36:37]
	v_pk_add_f32 v[24:25], v[24:25], v[38:39]
	v_cvt_pk_bf16_f32 v36, v22, v23
	v_cvt_pk_bf16_f32 v37, v24, v25
	global_store_dwordx4 v[40:41], v[22:25], off offset:128
	v_mov_b32_e32 v224, v36
	v_mov_b32_e32 v225, v37
	s_nop 0
	v_pk_mul_f32 v[22:23], v[22:23], v[22:23]
	v_pk_mul_f32 v[24:25], v[24:25], v[24:25]
	v_add_f32_e32 v22, v22, v23
	v_add_f32_e32 v22, v22, v24
	v_add_f32_e32 v27, v22, v25
	v_add_f32_e32 v26, v26, v27
	s_waitcnt lgkmcnt(0)
	v_mov_b32_e32 v36, v192
	v_mov_b32_e32 v37, v193
	v_mov_b32_e32 v38, v194
	v_mov_b32_e32 v39, v195
	v_pk_add_f32 v[22:23], v[18:19], v[36:37]
	v_pk_add_f32 v[24:25], v[20:21], v[38:39]
	v_pk_mul_f32 v[18:19], v[22:23], v[22:23]
	v_pk_mul_f32 v[20:21], v[24:25], v[24:25]
	v_add_f32_e32 v18, v18, v19
	v_add_f32_e32 v18, v18, v20
	v_add_f32_e32 v18, v18, v21
	v_add_f32_e32 v18, v26, v18
	ds_bpermute_b32 v19, v122, v18
	v_cvt_pk_bf16_f32 v20, v22, v23
	v_cvt_pk_bf16_f32 v21, v24, v25
	global_store_dwordx4 v[40:41], v[22:25], off offset:192
	v_mov_b32_e32 v226, v20
	v_mov_b32_e32 v227, v21
	s_nop 1
	v_lshl_add_u64 v[228:229], v[44:45], 0, v[230:231]
	v_permlane16_swap_b32_e32 v224, v226
	v_permlane16_swap_b32_e32 v225, v227
	global_store_dwordx4 v[228:229], v[224:227], off offset:64
	s_waitcnt lgkmcnt(0)
	v_add_f32_e32 v18, v18, v19
	ds_bpermute_b32 v19, v123, v18
	s_and_saveexec_b64 s[0:1], vcc
	s_cbranch_execz .LBB0_546
	s_waitcnt lgkmcnt(0)
	v_add_f32_e32 v20, v18, v19
	v_lshl_add_u64 v[18:19], v[34:35], 2, s[10:11]
	global_atomic_add_f32 v[18:19], v20, off
.LBB0_546:
	s_or_b64 exec, exec, s[0:1]
	v_or_b32_e32 v114, 0x70, v114
	v_lshlrev_b64 v[22:23], 12, v[114:115]
	s_waitcnt lgkmcnt(0)
	v_lshl_add_u64 v[18:19], v[132:133], 0, v[22:23]
	v_lshl_add_u64 v[24:25], v[18:19], 0, v[118:119]
	s_nop 0
	v_lshlrev_b64 v[26:27], 11, v[114:115]
	v_lshl_add_u64 v[22:23], v[130:131], 0, v[22:23]
	v_lshl_add_u64 v[26:27], s[8:9], 0, v[26:27]
	v_lshl_add_u64 v[22:23], v[22:23], 0, v[118:119]
	v_lshl_add_u64 v[26:27], v[116:117], 1, v[26:27]
	s_waitcnt vmcnt(6) lgkmcnt(0)
	v_mov_b32_e32 v18, v196
	v_mov_b32_e32 v19, v197
	v_mov_b32_e32 v20, v198
	v_mov_b32_e32 v21, v199
	v_pk_add_f32 v[14:15], v[14:15], v[18:19]
	v_pk_add_f32 v[16:17], v[16:17], v[20:21]
	v_cvt_pk_bf16_f32 v18, v14, v15
	v_cvt_pk_bf16_f32 v19, v16, v17
	global_store_dwordx4 v[22:23], v[14:17], off
	v_mov_b32_e32 v220, v18
	v_mov_b32_e32 v221, v19
	s_nop 0
	v_pk_mul_f32 v[14:15], v[14:15], v[14:15]
	v_pk_mul_f32 v[16:17], v[16:17], v[16:17]
	v_add_f32_e32 v14, v14, v15
	v_add_f32_e32 v14, v14, v16
	v_add_f32_e32 v14, v14, v17
	s_waitcnt lgkmcnt(0)
	v_mov_b32_e32 v18, v200
	v_mov_b32_e32 v19, v201
	v_mov_b32_e32 v20, v202
	v_mov_b32_e32 v21, v203
	v_pk_add_f32 v[10:11], v[10:11], v[18:19]
	v_pk_add_f32 v[12:13], v[12:13], v[20:21]
	v_cvt_pk_bf16_f32 v18, v10, v11
	v_cvt_pk_bf16_f32 v19, v12, v13
	global_store_dwordx4 v[22:23], v[10:13], off offset:64
	v_mov_b32_e32 v222, v18
	v_mov_b32_e32 v223, v19
	v_mbcnt_lo_u32_b32 v230, -1, 0
	v_mbcnt_hi_u32_b32 v230, -1, v230
	v_and_b32_e32 v230, 16, v230
	v_lshrrev_b32_e32 v228, 1, v230
	v_add_u32_e32 v230, v230, v228
	v_mov_b32_e32 v231, 0
	v_lshl_add_u64 v[228:229], v[26:27], 0, v[230:231]
	v_permlane16_swap_b32_e32 v220, v222
	v_permlane16_swap_b32_e32 v221, v223
	global_store_dwordx4 v[228:229], v[220:223], off
	s_nop 0
	v_pk_mul_f32 v[10:11], v[10:11], v[10:11]
	v_pk_mul_f32 v[12:13], v[12:13], v[12:13]
	v_add_f32_e32 v10, v10, v11
	v_add_f32_e32 v10, v10, v12
	v_add_f32_e32 v10, v10, v13
	v_add_f32_e32 v10, v14, v10
	s_waitcnt lgkmcnt(0)
	v_mov_b32_e32 v18, v204
	v_mov_b32_e32 v19, v205
	v_mov_b32_e32 v20, v206
	v_mov_b32_e32 v21, v207
	v_pk_add_f32 v[6:7], v[6:7], v[18:19]
	v_pk_add_f32 v[8:9], v[8:9], v[20:21]
	v_cvt_pk_bf16_f32 v18, v6, v7
	v_cvt_pk_bf16_f32 v19, v8, v9
	global_store_dwordx4 v[22:23], v[6:9], off offset:128
	v_mov_b32_e32 v224, v18
	v_mov_b32_e32 v225, v19
	s_nop 0
	v_pk_mul_f32 v[6:7], v[6:7], v[6:7]
	v_pk_mul_f32 v[8:9], v[8:9], v[8:9]
	v_add_f32_e32 v6, v6, v7
	v_add_f32_e32 v6, v6, v8
	v_add_f32_e32 v11, v6, v9
	v_add_f32_e32 v10, v10, v11
	s_waitcnt lgkmcnt(0)
	v_mov_b32_e32 v18, v208
	v_mov_b32_e32 v19, v209
	v_mov_b32_e32 v20, v210
	v_mov_b32_e32 v21, v211
	v_pk_add_f32 v[6:7], v[2:3], v[18:19]
	v_pk_add_f32 v[8:9], v[4:5], v[20:21]
	v_pk_mul_f32 v[2:3], v[6:7], v[6:7]
	v_pk_mul_f32 v[4:5], v[8:9], v[8:9]
	v_add_f32_e32 v2, v2, v3
	v_add_f32_e32 v2, v2, v4
	v_add_f32_e32 v2, v2, v5
	v_add_f32_e32 v2, v10, v2
	ds_bpermute_b32 v3, v122, v2
	v_cvt_pk_bf16_f32 v4, v6, v7
	v_cvt_pk_bf16_f32 v5, v8, v9
	global_store_dwordx4 v[22:23], v[6:9], off offset:192
	v_mov_b32_e32 v226, v4
	v_mov_b32_e32 v227, v5
	s_nop 1
	v_lshl_add_u64 v[228:229], v[26:27], 0, v[230:231]
	v_permlane16_swap_b32_e32 v224, v226
	v_permlane16_swap_b32_e32 v225, v227
	global_store_dwordx4 v[228:229], v[224:227], off offset:64
	s_waitcnt lgkmcnt(0)
	v_add_f32_e32 v2, v2, v3
	ds_bpermute_b32 v3, v123, v2
	s_and_saveexec_b64 s[0:1], vcc
	s_cbranch_execz .LBB0_529
	s_waitcnt lgkmcnt(0)
	v_add_f32_e32 v4, v2, v3
	v_lshl_add_u64 v[2:3], v[114:115], 2, s[10:11]
	global_atomic_add_f32 v[2:3], v4, off
	s_branch .LBB0_529

.LBB0_587:
	s_mul_i32 s43, s1, 0x6000
	s_add_i32 s50, s43, 0xffffa000
	s_cmp_lg_u32 s1, 0
	s_cselect_b32 s50, s50, 0xc000
	v_add_u32_e32 v148, s50, v143
	v_lshl_add_u64 v[144:145], v[136:137], 0, s[48:49]
	v_readfirstlane_b32 s50, v148
	v_add_u32_e32 v149, 0x1000, v148
	v_lshl_add_u64 v[146:147], v[144:145], 0, s[24:25]
	s_mov_b32 m0, s50
	v_readfirstlane_b32 s50, v149
	v_add_u32_e32 v149, 0x2000, v148
	s_waitcnt vmcnt(6)
	s_barrier
	global_load_lds_dwordx4 v[146:147], off
	v_lshl_add_u64 v[146:147], v[144:145], 0, s[26:27]
	s_mov_b32 m0, s50
	v_readfirstlane_b32 s50, v149
	global_load_lds_dwordx4 v[146:147], off
	v_lshl_add_u64 v[146:147], v[144:145], 0, s[28:29]
	s_mov_b32 m0, s50
	v_lshl_add_u64 v[144:145], v[144:145], 0, s[30:31]
	global_load_lds_dwordx4 v[146:147], off
	v_add_u32_e32 v146, 0x3000, v148
	v_add_u32_e32 v149, 0x4000, v148
	v_readfirstlane_b32 s50, v146
	s_mov_b32 m0, s50
	v_readfirstlane_b32 s50, v149
	global_load_lds_dwordx4 v[144:145], off
	v_lshl_add_u64 v[144:145], v[134:135], 0, s[48:49]
	v_lshl_add_u64 v[146:147], v[144:145], 0, s[34:35]
	s_mov_b32 m0, s50
	v_lshl_add_u64 v[144:145], v[144:145], 0, s[44:45]
	global_load_lds_dwordx4 v[146:147], off
	v_add_u32_e32 v146, 0x5000, v148
	s_add_i32 s43, s43, 0
	v_readfirstlane_b32 s50, v146
	s_mov_b32 m0, s50
	v_add3_u32 v156, s43, v140, v142
	global_load_lds_dwordx4 v[144:145], off
	v_add3_u32 v176, s43, v141, v142
	ds_read_b128 v[144:147], v156 offset:16384
	ds_read_b128 v[148:151], v156 offset:17408
	ds_read_b128 v[152:155], v156 offset:18432
	ds_read_b128 v[156:159], v156 offset:19456
	ds_read_b128 v[160:163], v176
	ds_read_b128 v[164:167], v176 offset:1024
	ds_read_b128 v[168:171], v176 offset:2048
	ds_read_b128 v[172:175], v176 offset:3072
	s_setprio 1
	s_waitcnt lgkmcnt(0)
	v_mfma_f32_16x16x32_bf16 v[126:129], v[144:147], v[160:163], v[126:129]
	v_mfma_f32_16x16x32_bf16 v[122:125], v[148:151], v[160:163], v[122:125]
	v_mfma_f32_16x16x32_bf16 v[118:121], v[152:155], v[160:163], v[118:121]
	v_mfma_f32_16x16x32_bf16 v[114:117], v[156:159], v[160:163], v[114:117]
	v_mfma_f32_16x16x32_bf16 v[110:113], v[144:147], v[164:167], v[110:113]
	v_mfma_f32_16x16x32_bf16 v[106:109], v[148:151], v[164:167], v[106:109]
	v_mfma_f32_16x16x32_bf16 v[102:105], v[152:155], v[164:167], v[102:105]
	v_mfma_f32_16x16x32_bf16 v[98:101], v[156:159], v[164:167], v[98:101]
	v_mfma_f32_16x16x32_bf16 v[94:97], v[144:147], v[168:171], v[94:97]
	v_mfma_f32_16x16x32_bf16 v[90:93], v[148:151], v[168:171], v[90:93]
	v_mfma_f32_16x16x32_bf16 v[86:89], v[152:155], v[168:171], v[86:89]
	v_mfma_f32_16x16x32_bf16 v[82:85], v[156:159], v[168:171], v[82:85]
	v_mfma_f32_16x16x32_bf16 v[78:81], v[144:147], v[172:175], v[78:81]
	v_mfma_f32_16x16x32_bf16 v[74:77], v[148:151], v[172:175], v[74:77]
	v_mfma_f32_16x16x32_bf16 v[70:73], v[152:155], v[172:175], v[70:73]
	v_mfma_f32_16x16x32_bf16 v[66:69], v[156:159], v[172:175], v[66:69]
	s_setprio 0
	ds_read_b128 v[160:163], v176 offset:4096
	ds_read_b128 v[164:167], v176 offset:5120
	ds_read_b128 v[168:171], v176 offset:6144
	ds_read_b128 v[172:175], v176 offset:7168
	s_setprio 1
	s_waitcnt lgkmcnt(0)
	v_mfma_f32_16x16x32_bf16 v[62:65], v[144:147], v[160:163], v[62:65]
	v_mfma_f32_16x16x32_bf16 v[58:61], v[148:151], v[160:163], v[58:61]
	v_mfma_f32_16x16x32_bf16 v[54:57], v[152:155], v[160:163], v[54:57]
	v_mfma_f32_16x16x32_bf16 v[50:53], v[156:159], v[160:163], v[50:53]
	v_mfma_f32_16x16x32_bf16 v[46:49], v[144:147], v[164:167], v[46:49]
	v_mfma_f32_16x16x32_bf16 v[42:45], v[148:151], v[164:167], v[42:45]
	v_mfma_f32_16x16x32_bf16 v[38:41], v[152:155], v[164:167], v[38:41]
	v_mfma_f32_16x16x32_bf16 v[34:37], v[156:159], v[164:167], v[34:37]
	v_mfma_f32_16x16x32_bf16 v[30:33], v[144:147], v[168:171], v[30:33]
	v_mfma_f32_16x16x32_bf16 v[26:29], v[148:151], v[168:171], v[26:29]
	v_mfma_f32_16x16x32_bf16 v[22:25], v[152:155], v[168:171], v[22:25]
	v_mfma_f32_16x16x32_bf16 v[18:21], v[156:159], v[168:171], v[18:21]
	v_mfma_f32_16x16x32_bf16 v[14:17], v[144:147], v[172:175], v[14:17]
	v_mfma_f32_16x16x32_bf16 v[10:13], v[148:151], v[172:175], v[10:13]
	v_mfma_f32_16x16x32_bf16 v[6:9], v[152:155], v[172:175], v[6:9]
	v_mfma_f32_16x16x32_bf16 v[2:5], v[156:159], v[172:175], v[2:5]
	s_setprio 0
	s_add_i32 s43, s1, 1
	s_cmp_lg_u32 s1, 2
	s_cselect_b32 s1, s43, 0
	s_add_u32 s48, s48, 64
	s_addc_u32 s49, s49, 0
	s_cmpk_eq_i32 s48, 0x1f80
	s_cbranch_scc0 .LBB0_587
	s_mul_i32 s43, s1, 0x6000
	s_add_i32 s48, s43, 0
	v_add3_u32 v143, s48, v140, v142
	s_waitcnt vmcnt(6)
	s_barrier
	ds_read_b128 v[134:137], v143 offset:16384
	ds_read_b128 v[144:147], v143 offset:17408
	ds_read_b128 v[148:151], v143 offset:18432
	ds_read_b128 v[152:155], v143 offset:19456
	v_add3_u32 v143, s48, v141, v142
	ds_read_b128 v[156:159], v143
	ds_read_b128 v[160:163], v143 offset:1024
	ds_read_b128 v[164:167], v143 offset:2048
	ds_read_b128 v[168:171], v143 offset:3072
	s_lshl_b64 s[46:47], s[46:47], 8
	s_setprio 1
	s_waitcnt lgkmcnt(0)
	v_mfma_f32_16x16x32_bf16 v[118:121], v[148:151], v[156:159], v[118:121]
	v_mfma_f32_16x16x32_bf16 v[114:117], v[152:155], v[156:159], v[114:117]
	v_mfma_f32_16x16x32_bf16 v[110:113], v[134:137], v[160:163], v[110:113]
	v_mfma_f32_16x16x32_bf16 v[106:109], v[144:147], v[160:163], v[106:109]
	v_mfma_f32_16x16x32_bf16 v[102:105], v[148:151], v[160:163], v[102:105]
	v_mfma_f32_16x16x32_bf16 v[98:101], v[152:155], v[160:163], v[98:101]
	v_mfma_f32_16x16x32_bf16 v[94:97], v[134:137], v[164:167], v[94:97]
	v_mfma_f32_16x16x32_bf16 v[90:93], v[144:147], v[164:167], v[90:93]
	v_mfma_f32_16x16x32_bf16 v[86:89], v[148:151], v[164:167], v[86:89]
	v_mfma_f32_16x16x32_bf16 v[82:85], v[152:155], v[164:167], v[82:85]
	v_mfma_f32_16x16x32_bf16 v[78:81], v[134:137], v[168:171], v[78:81]
	v_mfma_f32_16x16x32_bf16 v[74:77], v[144:147], v[168:171], v[74:77]
	v_mfma_f32_16x16x32_bf16 v[70:73], v[148:151], v[168:171], v[70:73]
	v_mfma_f32_16x16x32_bf16 v[66:69], v[152:155], v[168:171], v[66:69]
	v_mfma_f32_16x16x32_bf16 v[126:129], v[134:137], v[156:159], v[126:129]
	v_mfma_f32_16x16x32_bf16 v[122:125], v[144:147], v[156:159], v[122:125]
	s_setprio 0
	ds_read_b128 v[156:159], v143 offset:4096
	ds_read_b128 v[160:163], v143 offset:5120
	ds_read_b128 v[164:167], v143 offset:6144
	ds_read_b128 v[168:171], v143 offset:7168
	s_setprio 1
	s_waitcnt lgkmcnt(0)
	v_mfma_f32_16x16x32_bf16 v[62:65], v[134:137], v[156:159], v[62:65]
	v_mfma_f32_16x16x32_bf16 v[58:61], v[144:147], v[156:159], v[58:61]
	v_mfma_f32_16x16x32_bf16 v[54:57], v[148:151], v[156:159], v[54:57]
	v_mfma_f32_16x16x32_bf16 v[50:53], v[152:155], v[156:159], v[50:53]
	v_mfma_f32_16x16x32_bf16 v[46:49], v[134:137], v[160:163], v[46:49]
	v_mfma_f32_16x16x32_bf16 v[42:45], v[144:147], v[160:163], v[42:45]
	v_mfma_f32_16x16x32_bf16 v[38:41], v[148:151], v[160:163], v[38:41]
	v_mfma_f32_16x16x32_bf16 v[34:37], v[152:155], v[160:163], v[34:37]
	v_mfma_f32_16x16x32_bf16 v[30:33], v[134:137], v[164:167], v[30:33]
	v_mfma_f32_16x16x32_bf16 v[26:29], v[144:147], v[164:167], v[26:29]
	v_mfma_f32_16x16x32_bf16 v[22:25], v[148:151], v[164:167], v[22:25]
	v_mfma_f32_16x16x32_bf16 v[18:21], v[152:155], v[164:167], v[18:21]
	v_mfma_f32_16x16x32_bf16 v[14:17], v[134:137], v[168:171], v[14:17]
	v_mfma_f32_16x16x32_bf16 v[10:13], v[144:147], v[168:171], v[10:13]
	v_mfma_f32_16x16x32_bf16 v[6:9], v[148:151], v[168:171], v[6:9]
	v_mfma_f32_16x16x32_bf16 v[2:5], v[152:155], v[168:171], v[2:5]
	s_setprio 0
	s_addk_i32 s43, 0x6000
	s_cmp_lg_u32 s1, 2
	s_cselect_b32 s1, s43, 0
	s_add_i32 s1, s1, 0
	v_add3_u32 v140, s1, v140, v142
	v_add3_u32 v168, s1, v141, v142
	s_waitcnt vmcnt(0)
	s_barrier
	ds_read_b128 v[134:137], v140 offset:16384
	ds_read_b128 v[144:147], v140 offset:17408
	ds_read_b128 v[148:151], v140 offset:18432
	ds_read_b128 v[152:155], v140 offset:19456
	ds_read_b128 v[140:143], v168
	ds_read_b128 v[156:159], v168 offset:1024
	ds_read_b128 v[160:163], v168 offset:2048
	ds_read_b128 v[164:167], v168 offset:3072
	s_setprio 1
	s_waitcnt lgkmcnt(0)
	v_mfma_f32_16x16x32_bf16 v[118:121], v[148:151], v[140:143], v[118:121]
	v_mfma_f32_16x16x32_bf16 v[110:113], v[134:137], v[156:159], v[110:113]
	v_mfma_f32_16x16x32_bf16 v[106:109], v[144:147], v[156:159], v[106:109]
	v_mfma_f32_16x16x32_bf16 v[102:105], v[148:151], v[156:159], v[102:105]
	v_mfma_f32_16x16x32_bf16 v[98:101], v[152:155], v[156:159], v[98:101]
	v_mfma_f32_16x16x32_bf16 v[94:97], v[134:137], v[160:163], v[94:97]
	v_mfma_f32_16x16x32_bf16 v[90:93], v[144:147], v[160:163], v[90:93]
	v_mfma_f32_16x16x32_bf16 v[86:89], v[148:151], v[160:163], v[86:89]
	v_mfma_f32_16x16x32_bf16 v[82:85], v[152:155], v[160:163], v[82:85]
	v_mfma_f32_16x16x32_bf16 v[78:81], v[134:137], v[164:167], v[78:81]
	v_mfma_f32_16x16x32_bf16 v[74:77], v[144:147], v[164:167], v[74:77]
	v_mfma_f32_16x16x32_bf16 v[70:73], v[148:151], v[164:167], v[70:73]
	v_mfma_f32_16x16x32_bf16 v[66:69], v[152:155], v[164:167], v[66:69]
	v_mfma_f32_16x16x32_bf16 v[126:129], v[134:137], v[140:143], v[126:129]
	v_mfma_f32_16x16x32_bf16 v[122:125], v[144:147], v[140:143], v[122:125]
	v_mfma_f32_16x16x32_bf16 v[140:143], v[152:155], v[140:143], v[114:117]
	s_setprio 0
	s_nop 1
	ds_read_b128 v[114:117], v168 offset:4096
	ds_read_b128 v[156:159], v168 offset:5120
	ds_read_b128 v[160:163], v168 offset:6144
	ds_read_b128 v[164:167], v168 offset:7168
	s_setprio 1
	s_waitcnt lgkmcnt(0)
	v_mfma_f32_16x16x32_bf16 v[62:65], v[134:137], v[114:117], v[62:65]
	v_mfma_f32_16x16x32_bf16 v[58:61], v[144:147], v[114:117], v[58:61]
	v_mfma_f32_16x16x32_bf16 v[54:57], v[148:151], v[114:117], v[54:57]
	v_mfma_f32_16x16x32_bf16 v[50:53], v[152:155], v[114:117], v[50:53]
	v_mfma_f32_16x16x32_bf16 v[46:49], v[134:137], v[156:159], v[46:49]
	v_mfma_f32_16x16x32_bf16 v[42:45], v[144:147], v[156:159], v[42:45]
	v_mfma_f32_16x16x32_bf16 v[38:41], v[148:151], v[156:159], v[38:41]
	v_mfma_f32_16x16x32_bf16 v[34:37], v[152:155], v[156:159], v[34:37]
	v_mfma_f32_16x16x32_bf16 v[30:33], v[134:137], v[160:163], v[30:33]
	v_mfma_f32_16x16x32_bf16 v[26:29], v[144:147], v[160:163], v[26:29]
	v_mfma_f32_16x16x32_bf16 v[22:25], v[148:151], v[160:163], v[22:25]
	v_mfma_f32_16x16x32_bf16 v[18:21], v[152:155], v[160:163], v[18:21]
	v_mfma_f32_16x16x32_bf16 v[14:17], v[134:137], v[164:167], v[14:17]
	v_mfma_f32_16x16x32_bf16 v[10:13], v[144:147], v[164:167], v[10:13]
	v_mfma_f32_16x16x32_bf16 v[6:9], v[148:151], v[164:167], v[6:9]
	v_mfma_f32_16x16x32_bf16 v[2:5], v[152:155], v[164:167], v[2:5]
	s_setprio 0
	v_lshl_add_u64 v[114:115], s[46:47], 0, v[132:133]
	v_lshl_or_b32 v116, s0, 7, v138
	v_lshlrev_b64 v[134:135], 12, v[114:115]
	s_waitcnt vmcnt(0)
	v_lshl_add_u64 v[134:135], v[130:131], 0, v[134:135]
	v_ashrrev_i32_e32 v117, 31, v116
	v_lshl_add_u64 v[148:149], v[116:117], 2, v[134:135]
	s_barrier
	v_mov_b32_e32 v212, v148
	v_mov_b32_e32 v213, v149
	global_load_dwordx4 v[180:183], v[212:213], off
	global_load_dwordx4 v[184:187], v[212:213], off offset:64
	global_load_dwordx4 v[188:191], v[212:213], off offset:128
	global_load_dwordx4 v[192:195], v[212:213], off offset:192
	s_mov_b32 s98, 0x10000
	s_mov_b32 s99, 0
	v_lshl_add_u64 v[214:215], v[212:213], 0, s[98:99]
	global_load_dwordx4 v[196:199], v[214:215], off
	global_load_dwordx4 v[200:203], v[214:215], off offset:64
	global_load_dwordx4 v[204:207], v[214:215], off offset:128
	global_load_dwordx4 v[208:211], v[214:215], off offset:192
	v_lshlrev_b64 v[144:145], 11, v[114:115]
	v_lshl_add_u64 v[144:145], s[8:9], 0, v[144:145]
	v_lshl_add_u64 v[150:151], v[116:117], 1, v[144:145]
	s_waitcnt vmcnt(4) lgkmcnt(0)
	v_mov_b32_e32 v134, v180
	v_mov_b32_e32 v135, v181
	v_mov_b32_e32 v136, v182
	v_mov_b32_e32 v137, v183
	v_pk_add_f32 v[126:127], v[126:127], v[134:135]
	v_pk_add_f32 v[128:129], v[128:129], v[136:137]
	v_cvt_pk_bf16_f32 v134, v126, v127
	v_cvt_pk_bf16_f32 v135, v128, v129
	global_store_dwordx4 v[148:149], v[126:129], off
	v_mov_b32_e32 v220, v134
	v_mov_b32_e32 v221, v135
	s_nop 0
	s_waitcnt lgkmcnt(0)
	v_mov_b32_e32 v134, v184
	v_mov_b32_e32 v135, v185
	v_mov_b32_e32 v136, v186
	v_mov_b32_e32 v137, v187
	v_pk_add_f32 v[122:123], v[122:123], v[134:135]
	v_pk_add_f32 v[124:125], v[124:125], v[136:137]
	v_cvt_pk_bf16_f32 v134, v122, v123
	v_cvt_pk_bf16_f32 v135, v124, v125
	global_store_dwordx4 v[148:149], v[122:125], off offset:64
	v_mov_b32_e32 v222, v134
	v_mov_b32_e32 v223, v135
	v_mbcnt_lo_u32_b32 v230, -1, 0
	v_mbcnt_hi_u32_b32 v230, -1, v230
	v_and_b32_e32 v230, 16, v230
	v_lshrrev_b32_e32 v228, 1, v230
	v_add_u32_e32 v230, v230, v228
	v_mov_b32_e32 v231, 0
	v_lshl_add_u64 v[228:229], v[150:151], 0, v[230:231]
	v_permlane16_swap_b32_e32 v220, v222
	v_permlane16_swap_b32_e32 v221, v223
	global_store_dwordx4 v[228:229], v[220:223], off
	s_nop 0
	s_waitcnt lgkmcnt(0)
	v_mov_b32_e32 v134, v188
	v_mov_b32_e32 v135, v189
	v_mov_b32_e32 v136, v190
	v_mov_b32_e32 v137, v191
	v_pk_add_f32 v[134:135], v[118:119], v[134:135]
	v_pk_add_f32 v[136:137], v[120:121], v[136:137]
	v_cvt_pk_bf16_f32 v118, v134, v135
	v_cvt_pk_bf16_f32 v119, v136, v137
	global_store_dwordx4 v[148:149], v[134:137], off offset:128
	v_mov_b32_e32 v224, v118
	v_mov_b32_e32 v225, v119
	s_nop 0
	v_and_b32_e32 v119, 64, v139
	v_xor_b32_e32 v118, 16, v139
	v_add_u32_e32 v121, 64, v119
	v_cmp_lt_i32_e64 s[0:1], v118, v121
	s_nop 1
	v_cndmask_b32_e64 v118, v139, v118, s[0:1]
	v_lshlrev_b32_e32 v120, 2, v118
	v_pk_mul_f32 v[118:119], v[126:127], v[126:127]
	v_pk_mul_f32 v[126:127], v[128:129], v[128:129]
	v_add_f32_e32 v118, v118, v119
	v_add_f32_e32 v118, v118, v126
	v_add_f32_e32 v126, v118, v127
	v_pk_mul_f32 v[118:119], v[122:123], v[122:123]
	v_pk_mul_f32 v[122:123], v[124:125], v[124:125]
	v_add_f32_e32 v118, v118, v119
	v_add_f32_e32 v118, v118, v122
	v_add_f32_e32 v118, v118, v123
	v_add_f32_e32 v128, v126, v118
	v_pk_mul_f32 v[118:119], v[134:135], v[134:135]
	v_pk_mul_f32 v[122:123], v[136:137], v[136:137]
	v_add_f32_e32 v118, v118, v119
	v_add_f32_e32 v118, v118, v122
	v_add_f32_e32 v129, v118, v123
	v_add_f32_e32 v128, v128, v129
	s_waitcnt lgkmcnt(0)
	v_mov_b32_e32 v144, v192
	v_mov_b32_e32 v145, v193
	v_mov_b32_e32 v146, v194
	v_mov_b32_e32 v147, v195
	v_pk_add_f32 v[122:123], v[140:141], v[144:145]
	v_pk_add_f32 v[124:125], v[142:143], v[146:147]
	v_pk_mul_f32 v[118:119], v[122:123], v[122:123]
	v_pk_mul_f32 v[126:127], v[124:125], v[124:125]
	v_add_f32_e32 v118, v118, v119
	v_add_f32_e32 v118, v118, v126
	v_add_f32_e32 v118, v118, v127
	v_add_f32_e32 v118, v128, v118
	ds_bpermute_b32 v119, v120, v118
	v_xor_b32_e32 v126, 32, v139
	v_cmp_lt_i32_e64 s[0:1], v126, v121
	global_store_dwordx4 v[148:149], v[122:125], off offset:192
	s_waitcnt lgkmcnt(0)
	v_add_f32_e32 v118, v118, v119
	v_cndmask_b32_e64 v121, v139, v126, s[0:1]
	v_lshlrev_b32_e32 v121, 2, v121
	ds_bpermute_b32 v119, v121, v118
	v_cvt_pk_bf16_f32 v122, v122, v123
	v_cvt_pk_bf16_f32 v123, v124, v125
	v_mov_b32_e32 v226, v122
	v_mov_b32_e32 v227, v123
	s_nop 1
	v_lshl_add_u64 v[228:229], v[150:151], 0, v[230:231]
	v_permlane16_swap_b32_e32 v224, v226
	v_permlane16_swap_b32_e32 v225, v227
	global_store_dwordx4 v[228:229], v[224:227], off offset:64
	s_and_saveexec_b64 s[0:1], vcc
	s_cbranch_execz .LBB0_590
	s_waitcnt lgkmcnt(0)
	v_add_f32_e32 v122, v118, v119
	v_lshl_add_u64 v[118:119], v[114:115], 2, s[10:11]
	global_atomic_add_f32 v[118:119], v122, off
.LBB0_590:
	s_or_b64 exec, exec, s[0:1]
	v_or_b32_e32 v118, 16, v114
	s_waitcnt lgkmcnt(0)
	v_mov_b32_e32 v119, v115
	v_lshlrev_b64 v[122:123], 12, v[118:119]
	v_lshl_add_u64 v[122:123], v[130:131], 0, v[122:123]
	v_lshl_add_u64 v[126:127], v[116:117], 2, v[122:123]
	s_mov_b32 s98, 0x20000
	s_mov_b32 s99, 0
	v_lshl_add_u64 v[214:215], v[212:213], 0, s[98:99]
	global_load_dwordx4 v[180:183], v[214:215], off
	global_load_dwordx4 v[184:187], v[214:215], off offset:64
	global_load_dwordx4 v[188:191], v[214:215], off offset:128
	global_load_dwordx4 v[192:195], v[214:215], off offset:192
	v_lshlrev_b64 v[128:129], 11, v[118:119]
	v_lshl_add_u64 v[128:129], s[8:9], 0, v[128:129]
	v_lshl_add_u64 v[128:129], v[116:117], 1, v[128:129]
	s_waitcnt vmcnt(10) lgkmcnt(0)
	v_mov_b32_e32 v122, v196
	v_mov_b32_e32 v123, v197
	v_mov_b32_e32 v124, v198
	v_mov_b32_e32 v125, v199
	v_pk_add_f32 v[110:111], v[110:111], v[122:123]
	v_pk_add_f32 v[112:113], v[112:113], v[124:125]
	v_cvt_pk_bf16_f32 v122, v110, v111
	v_cvt_pk_bf16_f32 v123, v112, v113
	global_store_dwordx4 v[126:127], v[110:113], off
	v_mov_b32_e32 v220, v122
	v_mov_b32_e32 v221, v123
	s_nop 0
	v_pk_mul_f32 v[110:111], v[110:111], v[110:111]
	v_pk_mul_f32 v[112:113], v[112:113], v[112:113]
	v_add_f32_e32 v110, v110, v111
	v_add_f32_e32 v110, v110, v112
	v_add_f32_e32 v110, v110, v113
	s_waitcnt lgkmcnt(0)
	v_mov_b32_e32 v122, v200
	v_mov_b32_e32 v123, v201
	v_mov_b32_e32 v124, v202
	v_mov_b32_e32 v125, v203
	v_pk_add_f32 v[106:107], v[106:107], v[122:123]
	v_pk_add_f32 v[108:109], v[108:109], v[124:125]
	v_cvt_pk_bf16_f32 v122, v106, v107
	v_cvt_pk_bf16_f32 v123, v108, v109
	global_store_dwordx4 v[126:127], v[106:109], off offset:64
	v_mov_b32_e32 v222, v122
	v_mov_b32_e32 v223, v123
	v_mbcnt_lo_u32_b32 v230, -1, 0
	v_mbcnt_hi_u32_b32 v230, -1, v230
	v_and_b32_e32 v230, 16, v230
	v_lshrrev_b32_e32 v228, 1, v230
	v_add_u32_e32 v230, v230, v228
	v_mov_b32_e32 v231, 0
	v_lshl_add_u64 v[228:229], v[128:129], 0, v[230:231]
	v_permlane16_swap_b32_e32 v220, v222
	v_permlane16_swap_b32_e32 v221, v223
	global_store_dwordx4 v[228:229], v[220:223], off
	s_nop 0
	v_pk_mul_f32 v[106:107], v[106:107], v[106:107]
	v_pk_mul_f32 v[108:109], v[108:109], v[108:109]
	v_add_f32_e32 v106, v106, v107
	v_add_f32_e32 v106, v106, v108
	v_add_f32_e32 v106, v106, v109
	v_add_f32_e32 v106, v110, v106
	s_waitcnt lgkmcnt(0)
	v_mov_b32_e32 v122, v204
	v_mov_b32_e32 v123, v205
	v_mov_b32_e32 v124, v206
	v_mov_b32_e32 v125, v207
	v_pk_add_f32 v[102:103], v[102:103], v[122:123]
	v_pk_add_f32 v[104:105], v[104:105], v[124:125]
	v_cvt_pk_bf16_f32 v122, v102, v103
	v_cvt_pk_bf16_f32 v123, v104, v105
	global_store_dwordx4 v[126:127], v[102:105], off offset:128
	v_mov_b32_e32 v224, v122
	v_mov_b32_e32 v225, v123
	s_nop 0
	v_pk_mul_f32 v[102:103], v[102:103], v[102:103]
	v_pk_mul_f32 v[104:105], v[104:105], v[104:105]
	v_add_f32_e32 v102, v102, v103
	v_add_f32_e32 v102, v102, v104
	v_add_f32_e32 v107, v102, v105
	v_add_f32_e32 v106, v106, v107
	s_waitcnt lgkmcnt(0)
	v_mov_b32_e32 v122, v208
	v_mov_b32_e32 v123, v209
	v_mov_b32_e32 v124, v210
	v_mov_b32_e32 v125, v211
	v_pk_add_f32 v[102:103], v[98:99], v[122:123]
	v_pk_add_f32 v[104:105], v[100:101], v[124:125]
	v_pk_mul_f32 v[98:99], v[102:103], v[102:103]
	v_pk_mul_f32 v[100:101], v[104:105], v[104:105]
	v_add_f32_e32 v98, v98, v99
	v_add_f32_e32 v98, v98, v100
	v_add_f32_e32 v98, v98, v101
	v_add_f32_e32 v98, v106, v98
	ds_bpermute_b32 v99, v120, v98
	v_cvt_pk_bf16_f32 v100, v102, v103
	v_cvt_pk_bf16_f32 v101, v104, v105
	global_store_dwordx4 v[126:127], v[102:105], off offset:192
	v_mov_b32_e32 v226, v100
	v_mov_b32_e32 v227, v101
	s_nop 1
	v_lshl_add_u64 v[228:229], v[128:129], 0, v[230:231]
	v_permlane16_swap_b32_e32 v224, v226
	v_permlane16_swap_b32_e32 v225, v227
	global_store_dwordx4 v[228:229], v[224:227], off offset:64
	s_waitcnt lgkmcnt(0)
	v_add_f32_e32 v98, v98, v99
	ds_bpermute_b32 v99, v121, v98
	s_and_saveexec_b64 s[0:1], vcc
	s_cbranch_execz .LBB0_592
	s_waitcnt lgkmcnt(0)
	v_add_f32_e32 v100, v98, v99
	v_lshl_add_u64 v[98:99], v[118:119], 2, s[10:11]
	global_atomic_add_f32 v[98:99], v100, off
.LBB0_592:
	s_or_b64 exec, exec, s[0:1]
	v_or_b32_e32 v98, 32, v114
	s_waitcnt lgkmcnt(0)
	v_mov_b32_e32 v99, v115
	v_lshlrev_b64 v[100:101], 12, v[98:99]
	v_lshl_add_u64 v[100:101], v[130:131], 0, v[100:101]
	v_lshl_add_u64 v[104:105], v[116:117], 2, v[100:101]
	s_mov_b32 s98, 0x30000
	s_mov_b32 s99, 0
	v_lshl_add_u64 v[214:215], v[212:213], 0, s[98:99]
	global_load_dwordx4 v[196:199], v[214:215], off
	global_load_dwordx4 v[200:203], v[214:215], off offset:64
	global_load_dwordx4 v[204:207], v[214:215], off offset:128
	global_load_dwordx4 v[208:211], v[214:215], off offset:192
	v_lshlrev_b64 v[106:107], 11, v[98:99]
	v_lshl_add_u64 v[106:107], s[8:9], 0, v[106:107]
	v_lshl_add_u64 v[106:107], v[116:117], 1, v[106:107]
	s_waitcnt vmcnt(10) lgkmcnt(0)
	v_mov_b32_e32 v100, v180
	v_mov_b32_e32 v101, v181
	v_mov_b32_e32 v102, v182
	v_mov_b32_e32 v103, v183
	v_pk_add_f32 v[94:95], v[94:95], v[100:101]
	v_pk_add_f32 v[96:97], v[96:97], v[102:103]
	v_cvt_pk_bf16_f32 v100, v94, v95
	v_cvt_pk_bf16_f32 v101, v96, v97
	global_store_dwordx4 v[104:105], v[94:97], off
	v_mov_b32_e32 v220, v100
	v_mov_b32_e32 v221, v101
	s_nop 0
	v_pk_mul_f32 v[94:95], v[94:95], v[94:95]
	v_pk_mul_f32 v[96:97], v[96:97], v[96:97]
	v_add_f32_e32 v94, v94, v95
	v_add_f32_e32 v94, v94, v96
	v_add_f32_e32 v94, v94, v97
	s_waitcnt lgkmcnt(0)
	v_mov_b32_e32 v100, v184
	v_mov_b32_e32 v101, v185
	v_mov_b32_e32 v102, v186
	v_mov_b32_e32 v103, v187
	v_pk_add_f32 v[90:91], v[90:91], v[100:101]
	v_pk_add_f32 v[92:93], v[92:93], v[102:103]
	v_cvt_pk_bf16_f32 v100, v90, v91
	v_cvt_pk_bf16_f32 v101, v92, v93
	global_store_dwordx4 v[104:105], v[90:93], off offset:64
	v_mov_b32_e32 v222, v100
	v_mov_b32_e32 v223, v101
	v_mbcnt_lo_u32_b32 v230, -1, 0
	v_mbcnt_hi_u32_b32 v230, -1, v230
	v_and_b32_e32 v230, 16, v230
	v_lshrrev_b32_e32 v228, 1, v230
	v_add_u32_e32 v230, v230, v228
	v_mov_b32_e32 v231, 0
	v_lshl_add_u64 v[228:229], v[106:107], 0, v[230:231]
	v_permlane16_swap_b32_e32 v220, v222
	v_permlane16_swap_b32_e32 v221, v223
	global_store_dwordx4 v[228:229], v[220:223], off
	s_nop 0
	v_pk_mul_f32 v[90:91], v[90:91], v[90:91]
	v_pk_mul_f32 v[92:93], v[92:93], v[92:93]
	v_add_f32_e32 v90, v90, v91
	v_add_f32_e32 v90, v90, v92
	v_add_f32_e32 v90, v90, v93
	v_add_f32_e32 v90, v94, v90
	s_waitcnt lgkmcnt(0)
	v_mov_b32_e32 v100, v188
	v_mov_b32_e32 v101, v189
	v_mov_b32_e32 v102, v190
	v_mov_b32_e32 v103, v191
	v_pk_add_f32 v[86:87], v[86:87], v[100:101]
	v_pk_add_f32 v[88:89], v[88:89], v[102:103]
	v_cvt_pk_bf16_f32 v100, v86, v87
	v_cvt_pk_bf16_f32 v101, v88, v89
	global_store_dwordx4 v[104:105], v[86:89], off offset:128
	v_mov_b32_e32 v224, v100
	v_mov_b32_e32 v225, v101
	s_nop 0
	v_pk_mul_f32 v[86:87], v[86:87], v[86:87]
	v_pk_mul_f32 v[88:89], v[88:89], v[88:89]
	v_add_f32_e32 v86, v86, v87
	v_add_f32_e32 v86, v86, v88
	v_add_f32_e32 v91, v86, v89
	v_add_f32_e32 v90, v90, v91
	s_waitcnt lgkmcnt(0)
	v_mov_b32_e32 v100, v192
	v_mov_b32_e32 v101, v193
	v_mov_b32_e32 v102, v194
	v_mov_b32_e32 v103, v195
	v_pk_add_f32 v[86:87], v[82:83], v[100:101]
	v_pk_add_f32 v[88:89], v[84:85], v[102:103]
	v_pk_mul_f32 v[82:83], v[86:87], v[86:87]
	v_pk_mul_f32 v[84:85], v[88:89], v[88:89]
	v_add_f32_e32 v82, v82, v83
	v_add_f32_e32 v82, v82, v84
	v_add_f32_e32 v82, v82, v85
	v_add_f32_e32 v82, v90, v82
	ds_bpermute_b32 v83, v120, v82
	v_cvt_pk_bf16_f32 v84, v86, v87
	v_cvt_pk_bf16_f32 v85, v88, v89
	global_store_dwordx4 v[104:105], v[86:89], off offset:192
	v_mov_b32_e32 v226, v84
	v_mov_b32_e32 v227, v85
	s_nop 1
	v_lshl_add_u64 v[228:229], v[106:107], 0, v[230:231]
	v_permlane16_swap_b32_e32 v224, v226
	v_permlane16_swap_b32_e32 v225, v227
	global_store_dwordx4 v[228:229], v[224:227], off offset:64
	s_waitcnt lgkmcnt(0)
	v_add_f32_e32 v82, v82, v83
	ds_bpermute_b32 v83, v121, v82
	s_and_saveexec_b64 s[0:1], vcc
	s_cbranch_execz .LBB0_594
	s_waitcnt lgkmcnt(0)
	v_add_f32_e32 v84, v82, v83
	v_lshl_add_u64 v[82:83], v[98:99], 2, s[10:11]
	global_atomic_add_f32 v[82:83], v84, off
.LBB0_594:
	s_or_b64 exec, exec, s[0:1]
	v_or_b32_e32 v82, 48, v114
	s_waitcnt lgkmcnt(0)
	v_mov_b32_e32 v83, v115
	v_lshlrev_b64 v[84:85], 12, v[82:83]
	v_lshl_add_u64 v[84:85], v[130:131], 0, v[84:85]
	v_lshl_add_u64 v[88:89], v[116:117], 2, v[84:85]
	s_mov_b32 s98, 0x40000
	s_mov_b32 s99, 0
	v_lshl_add_u64 v[214:215], v[212:213], 0, s[98:99]
	global_load_dwordx4 v[180:183], v[214:215], off
	global_load_dwordx4 v[184:187], v[214:215], off offset:64
	global_load_dwordx4 v[188:191], v[214:215], off offset:128
	global_load_dwordx4 v[192:195], v[214:215], off offset:192
	v_lshlrev_b64 v[90:91], 11, v[82:83]
	v_lshl_add_u64 v[90:91], s[8:9], 0, v[90:91]
	v_lshl_add_u64 v[90:91], v[116:117], 1, v[90:91]
	s_waitcnt vmcnt(10) lgkmcnt(0)
	v_mov_b32_e32 v84, v196
	v_mov_b32_e32 v85, v197
	v_mov_b32_e32 v86, v198
	v_mov_b32_e32 v87, v199
	v_pk_add_f32 v[78:79], v[78:79], v[84:85]
	v_pk_add_f32 v[80:81], v[80:81], v[86:87]
	v_cvt_pk_bf16_f32 v84, v78, v79
	v_cvt_pk_bf16_f32 v85, v80, v81
	global_store_dwordx4 v[88:89], v[78:81], off
	v_mov_b32_e32 v220, v84
	v_mov_b32_e32 v221, v85
	s_nop 0
	v_pk_mul_f32 v[78:79], v[78:79], v[78:79]
	v_pk_mul_f32 v[80:81], v[80:81], v[80:81]
	v_add_f32_e32 v78, v78, v79
	v_add_f32_e32 v78, v78, v80
	v_add_f32_e32 v78, v78, v81
	s_waitcnt lgkmcnt(0)
	v_mov_b32_e32 v84, v200
	v_mov_b32_e32 v85, v201
	v_mov_b32_e32 v86, v202
	v_mov_b32_e32 v87, v203
	v_pk_add_f32 v[74:75], v[74:75], v[84:85]
	v_pk_add_f32 v[76:77], v[76:77], v[86:87]
	v_cvt_pk_bf16_f32 v84, v74, v75
	v_cvt_pk_bf16_f32 v85, v76, v77
	global_store_dwordx4 v[88:89], v[74:77], off offset:64
	v_mov_b32_e32 v222, v84
	v_mov_b32_e32 v223, v85
	v_mbcnt_lo_u32_b32 v230, -1, 0
	v_mbcnt_hi_u32_b32 v230, -1, v230
	v_and_b32_e32 v230, 16, v230
	v_lshrrev_b32_e32 v228, 1, v230
	v_add_u32_e32 v230, v230, v228
	v_mov_b32_e32 v231, 0
	v_lshl_add_u64 v[228:229], v[90:91], 0, v[230:231]
	v_permlane16_swap_b32_e32 v220, v222
	v_permlane16_swap_b32_e32 v221, v223
	global_store_dwordx4 v[228:229], v[220:223], off
	s_nop 0
	v_pk_mul_f32 v[74:75], v[74:75], v[74:75]
	v_pk_mul_f32 v[76:77], v[76:77], v[76:77]
	v_add_f32_e32 v74, v74, v75
	v_add_f32_e32 v74, v74, v76
	v_add_f32_e32 v74, v74, v77
	v_add_f32_e32 v74, v78, v74
	s_waitcnt lgkmcnt(0)
	v_mov_b32_e32 v84, v204
	v_mov_b32_e32 v85, v205
	v_mov_b32_e32 v86, v206
	v_mov_b32_e32 v87, v207
	v_pk_add_f32 v[70:71], v[70:71], v[84:85]
	v_pk_add_f32 v[72:73], v[72:73], v[86:87]
	v_cvt_pk_bf16_f32 v84, v70, v71
	v_cvt_pk_bf16_f32 v85, v72, v73
	global_store_dwordx4 v[88:89], v[70:73], off offset:128
	v_mov_b32_e32 v224, v84
	v_mov_b32_e32 v225, v85
	s_nop 0
	v_pk_mul_f32 v[70:71], v[70:71], v[70:71]
	v_pk_mul_f32 v[72:73], v[72:73], v[72:73]
	v_add_f32_e32 v70, v70, v71
	v_add_f32_e32 v70, v70, v72
	v_add_f32_e32 v75, v70, v73
	v_add_f32_e32 v74, v74, v75
	s_waitcnt lgkmcnt(0)
	v_mov_b32_e32 v84, v208
	v_mov_b32_e32 v85, v209
	v_mov_b32_e32 v86, v210
	v_mov_b32_e32 v87, v211
	v_pk_add_f32 v[70:71], v[66:67], v[84:85]
	v_pk_add_f32 v[72:73], v[68:69], v[86:87]
	v_pk_mul_f32 v[66:67], v[70:71], v[70:71]
	v_pk_mul_f32 v[68:69], v[72:73], v[72:73]
	v_add_f32_e32 v66, v66, v67
	v_add_f32_e32 v66, v66, v68
	v_add_f32_e32 v66, v66, v69
	v_add_f32_e32 v66, v74, v66
	ds_bpermute_b32 v67, v120, v66
	v_cvt_pk_bf16_f32 v68, v70, v71
	v_cvt_pk_bf16_f32 v69, v72, v73
	global_store_dwordx4 v[88:89], v[70:73], off offset:192
	v_mov_b32_e32 v226, v68
	v_mov_b32_e32 v227, v69
	s_nop 1
	v_lshl_add_u64 v[228:229], v[90:91], 0, v[230:231]
	v_permlane16_swap_b32_e32 v224, v226
	v_permlane16_swap_b32_e32 v225, v227
	global_store_dwordx4 v[228:229], v[224:227], off offset:64
	s_waitcnt lgkmcnt(0)
	v_add_f32_e32 v66, v66, v67
	ds_bpermute_b32 v67, v121, v66
	s_and_saveexec_b64 s[0:1], vcc
	s_cbranch_execz .LBB0_596
	s_waitcnt lgkmcnt(0)
	v_add_f32_e32 v68, v66, v67
	v_lshl_add_u64 v[66:67], v[82:83], 2, s[10:11]
	global_atomic_add_f32 v[66:67], v68, off
.LBB0_596:
	s_or_b64 exec, exec, s[0:1]
	v_or_b32_e32 v66, 64, v114
	s_waitcnt lgkmcnt(0)
	v_mov_b32_e32 v67, v115
	v_lshlrev_b64 v[68:69], 12, v[66:67]
	v_lshl_add_u64 v[68:69], v[130:131], 0, v[68:69]
	v_lshl_add_u64 v[72:73], v[116:117], 2, v[68:69]
	s_mov_b32 s98, 0x50000
	s_mov_b32 s99, 0
	v_lshl_add_u64 v[214:215], v[212:213], 0, s[98:99]
	global_load_dwordx4 v[196:199], v[214:215], off
	global_load_dwordx4 v[200:203], v[214:215], off offset:64
	global_load_dwordx4 v[204:207], v[214:215], off offset:128
	global_load_dwordx4 v[208:211], v[214:215], off offset:192
	v_lshlrev_b64 v[74:75], 11, v[66:67]
	v_lshl_add_u64 v[74:75], s[8:9], 0, v[74:75]
	v_lshl_add_u64 v[74:75], v[116:117], 1, v[74:75]
	s_waitcnt vmcnt(10) lgkmcnt(0)
	v_mov_b32_e32 v68, v180
	v_mov_b32_e32 v69, v181
	v_mov_b32_e32 v70, v182
	v_mov_b32_e32 v71, v183
	v_pk_add_f32 v[62:63], v[62:63], v[68:69]
	v_pk_add_f32 v[64:65], v[64:65], v[70:71]
	v_cvt_pk_bf16_f32 v68, v62, v63
	v_cvt_pk_bf16_f32 v69, v64, v65
	global_store_dwordx4 v[72:73], v[62:65], off
	v_mov_b32_e32 v220, v68
	v_mov_b32_e32 v221, v69
	s_nop 0
	v_pk_mul_f32 v[62:63], v[62:63], v[62:63]
	v_pk_mul_f32 v[64:65], v[64:65], v[64:65]
	v_add_f32_e32 v62, v62, v63
	v_add_f32_e32 v62, v62, v64
	v_add_f32_e32 v62, v62, v65
	s_waitcnt lgkmcnt(0)
	v_mov_b32_e32 v68, v184
	v_mov_b32_e32 v69, v185
	v_mov_b32_e32 v70, v186
	v_mov_b32_e32 v71, v187
	v_pk_add_f32 v[58:59], v[58:59], v[68:69]
	v_pk_add_f32 v[60:61], v[60:61], v[70:71]
	v_cvt_pk_bf16_f32 v68, v58, v59
	v_cvt_pk_bf16_f32 v69, v60, v61
	global_store_dwordx4 v[72:73], v[58:61], off offset:64
	v_mov_b32_e32 v222, v68
	v_mov_b32_e32 v223, v69
	v_mbcnt_lo_u32_b32 v230, -1, 0
	v_mbcnt_hi_u32_b32 v230, -1, v230
	v_and_b32_e32 v230, 16, v230
	v_lshrrev_b32_e32 v228, 1, v230
	v_add_u32_e32 v230, v230, v228
	v_mov_b32_e32 v231, 0
	v_lshl_add_u64 v[228:229], v[74:75], 0, v[230:231]
	v_permlane16_swap_b32_e32 v220, v222
	v_permlane16_swap_b32_e32 v221, v223
	global_store_dwordx4 v[228:229], v[220:223], off
	s_nop 0
	v_pk_mul_f32 v[58:59], v[58:59], v[58:59]
	v_pk_mul_f32 v[60:61], v[60:61], v[60:61]
	v_add_f32_e32 v58, v58, v59
	v_add_f32_e32 v58, v58, v60
	v_add_f32_e32 v58, v58, v61
	v_add_f32_e32 v58, v62, v58
	s_waitcnt lgkmcnt(0)
	v_mov_b32_e32 v68, v188
	v_mov_b32_e32 v69, v189
	v_mov_b32_e32 v70, v190
	v_mov_b32_e32 v71, v191
	v_pk_add_f32 v[54:55], v[54:55], v[68:69]
	v_pk_add_f32 v[56:57], v[56:57], v[70:71]
	v_cvt_pk_bf16_f32 v68, v54, v55
	v_cvt_pk_bf16_f32 v69, v56, v57
	global_store_dwordx4 v[72:73], v[54:57], off offset:128
	v_mov_b32_e32 v224, v68
	v_mov_b32_e32 v225, v69
	s_nop 0
	v_pk_mul_f32 v[54:55], v[54:55], v[54:55]
	v_pk_mul_f32 v[56:57], v[56:57], v[56:57]
	v_add_f32_e32 v54, v54, v55
	v_add_f32_e32 v54, v54, v56
	v_add_f32_e32 v59, v54, v57
	v_add_f32_e32 v58, v58, v59
	s_waitcnt lgkmcnt(0)
	v_mov_b32_e32 v68, v192
	v_mov_b32_e32 v69, v193
	v_mov_b32_e32 v70, v194
	v_mov_b32_e32 v71, v195
	v_pk_add_f32 v[54:55], v[50:51], v[68:69]
	v_pk_add_f32 v[56:57], v[52:53], v[70:71]
	v_pk_mul_f32 v[50:51], v[54:55], v[54:55]
	v_pk_mul_f32 v[52:53], v[56:57], v[56:57]
	v_add_f32_e32 v50, v50, v51
	v_add_f32_e32 v50, v50, v52
	v_add_f32_e32 v50, v50, v53
	v_add_f32_e32 v50, v58, v50
	ds_bpermute_b32 v51, v120, v50
	v_cvt_pk_bf16_f32 v52, v54, v55
	v_cvt_pk_bf16_f32 v53, v56, v57
	global_store_dwordx4 v[72:73], v[54:57], off offset:192
	v_mov_b32_e32 v226, v52
	v_mov_b32_e32 v227, v53
	s_nop 1
	v_lshl_add_u64 v[228:229], v[74:75], 0, v[230:231]
	v_permlane16_swap_b32_e32 v224, v226
	v_permlane16_swap_b32_e32 v225, v227
	global_store_dwordx4 v[228:229], v[224:227], off offset:64
	s_waitcnt lgkmcnt(0)
	v_add_f32_e32 v50, v50, v51
	ds_bpermute_b32 v51, v121, v50
	s_and_saveexec_b64 s[0:1], vcc
	s_cbranch_execz .LBB0_598
	s_waitcnt lgkmcnt(0)
	v_add_f32_e32 v52, v50, v51
	v_lshl_add_u64 v[50:51], v[66:67], 2, s[10:11]
	global_atomic_add_f32 v[50:51], v52, off
.LBB0_598:
	s_or_b64 exec, exec, s[0:1]
	v_or_b32_e32 v50, 0x50, v114
	s_waitcnt lgkmcnt(0)
	v_mov_b32_e32 v51, v115
	v_lshlrev_b64 v[52:53], 12, v[50:51]
	v_lshl_add_u64 v[52:53], v[130:131], 0, v[52:53]
	v_lshl_add_u64 v[56:57], v[116:117], 2, v[52:53]
	s_mov_b32 s98, 0x60000
	s_mov_b32 s99, 0
	v_lshl_add_u64 v[214:215], v[212:213], 0, s[98:99]
	global_load_dwordx4 v[180:183], v[214:215], off
	global_load_dwordx4 v[184:187], v[214:215], off offset:64
	global_load_dwordx4 v[188:191], v[214:215], off offset:128
	global_load_dwordx4 v[192:195], v[214:215], off offset:192
	v_lshlrev_b64 v[58:59], 11, v[50:51]
	v_lshl_add_u64 v[58:59], s[8:9], 0, v[58:59]
	v_lshl_add_u64 v[58:59], v[116:117], 1, v[58:59]
	s_waitcnt vmcnt(10) lgkmcnt(0)
	v_mov_b32_e32 v52, v196
	v_mov_b32_e32 v53, v197
	v_mov_b32_e32 v54, v198
	v_mov_b32_e32 v55, v199
	v_pk_add_f32 v[46:47], v[46:47], v[52:53]
	v_pk_add_f32 v[48:49], v[48:49], v[54:55]
	v_cvt_pk_bf16_f32 v52, v46, v47
	v_cvt_pk_bf16_f32 v53, v48, v49
	global_store_dwordx4 v[56:57], v[46:49], off
	v_mov_b32_e32 v220, v52
	v_mov_b32_e32 v221, v53
	s_nop 0
	v_pk_mul_f32 v[46:47], v[46:47], v[46:47]
	v_pk_mul_f32 v[48:49], v[48:49], v[48:49]
	v_add_f32_e32 v46, v46, v47
	v_add_f32_e32 v46, v46, v48
	v_add_f32_e32 v46, v46, v49
	s_waitcnt lgkmcnt(0)
	v_mov_b32_e32 v52, v200
	v_mov_b32_e32 v53, v201
	v_mov_b32_e32 v54, v202
	v_mov_b32_e32 v55, v203
	v_pk_add_f32 v[42:43], v[42:43], v[52:53]
	v_pk_add_f32 v[44:45], v[44:45], v[54:55]
	v_cvt_pk_bf16_f32 v52, v42, v43
	v_cvt_pk_bf16_f32 v53, v44, v45
	global_store_dwordx4 v[56:57], v[42:45], off offset:64
	v_mov_b32_e32 v222, v52
	v_mov_b32_e32 v223, v53
	v_mbcnt_lo_u32_b32 v230, -1, 0
	v_mbcnt_hi_u32_b32 v230, -1, v230
	v_and_b32_e32 v230, 16, v230
	v_lshrrev_b32_e32 v228, 1, v230
	v_add_u32_e32 v230, v230, v228
	v_mov_b32_e32 v231, 0
	v_lshl_add_u64 v[228:229], v[58:59], 0, v[230:231]
	v_permlane16_swap_b32_e32 v220, v222
	v_permlane16_swap_b32_e32 v221, v223
	global_store_dwordx4 v[228:229], v[220:223], off
	s_nop 0
	v_pk_mul_f32 v[42:43], v[42:43], v[42:43]
	v_pk_mul_f32 v[44:45], v[44:45], v[44:45]
	v_add_f32_e32 v42, v42, v43
	v_add_f32_e32 v42, v42, v44
	v_add_f32_e32 v42, v42, v45
	v_add_f32_e32 v42, v46, v42
	s_waitcnt lgkmcnt(0)
	v_mov_b32_e32 v52, v204
	v_mov_b32_e32 v53, v205
	v_mov_b32_e32 v54, v206
	v_mov_b32_e32 v55, v207
	v_pk_add_f32 v[38:39], v[38:39], v[52:53]
	v_pk_add_f32 v[40:41], v[40:41], v[54:55]
	v_cvt_pk_bf16_f32 v52, v38, v39
	v_cvt_pk_bf16_f32 v53, v40, v41
	global_store_dwordx4 v[56:57], v[38:41], off offset:128
	v_mov_b32_e32 v224, v52
	v_mov_b32_e32 v225, v53
	s_nop 0
	v_pk_mul_f32 v[38:39], v[38:39], v[38:39]
	v_pk_mul_f32 v[40:41], v[40:41], v[40:41]
	v_add_f32_e32 v38, v38, v39
	v_add_f32_e32 v38, v38, v40
	v_add_f32_e32 v43, v38, v41
	v_add_f32_e32 v42, v42, v43
	s_waitcnt lgkmcnt(0)
	v_mov_b32_e32 v52, v208
	v_mov_b32_e32 v53, v209
	v_mov_b32_e32 v54, v210
	v_mov_b32_e32 v55, v211
	v_pk_add_f32 v[38:39], v[34:35], v[52:53]
	v_pk_add_f32 v[40:41], v[36:37], v[54:55]
	v_pk_mul_f32 v[34:35], v[38:39], v[38:39]
	v_pk_mul_f32 v[36:37], v[40:41], v[40:41]
	v_add_f32_e32 v34, v34, v35
	v_add_f32_e32 v34, v34, v36
	v_add_f32_e32 v34, v34, v37
	v_add_f32_e32 v34, v42, v34
	ds_bpermute_b32 v35, v120, v34
	v_cvt_pk_bf16_f32 v36, v38, v39
	v_cvt_pk_bf16_f32 v37, v40, v41
	global_store_dwordx4 v[56:57], v[38:41], off offset:192
	v_mov_b32_e32 v226, v36
	v_mov_b32_e32 v227, v37
	s_nop 1
	v_lshl_add_u64 v[228:229], v[58:59], 0, v[230:231]
	v_permlane16_swap_b32_e32 v224, v226
	v_permlane16_swap_b32_e32 v225, v227
	global_store_dwordx4 v[228:229], v[224:227], off offset:64
	s_waitcnt lgkmcnt(0)
	v_add_f32_e32 v34, v34, v35
	ds_bpermute_b32 v35, v121, v34
	s_and_saveexec_b64 s[0:1], vcc
	s_cbranch_execz .LBB0_600
	s_waitcnt lgkmcnt(0)
	v_add_f32_e32 v36, v34, v35
	v_lshl_add_u64 v[34:35], v[50:51], 2, s[10:11]
	global_atomic_add_f32 v[34:35], v36, off
.LBB0_600:
	s_or_b64 exec, exec, s[0:1]
	v_or_b32_e32 v34, 0x60, v114
	s_waitcnt lgkmcnt(0)
	v_mov_b32_e32 v35, v115
	v_lshlrev_b64 v[36:37], 12, v[34:35]
	v_lshl_add_u64 v[36:37], v[130:131], 0, v[36:37]
	v_lshl_add_u64 v[40:41], v[116:117], 2, v[36:37]
	s_mov_b32 s98, 0x70000
	s_mov_b32 s99, 0
	v_lshl_add_u64 v[214:215], v[212:213], 0, s[98:99]
	global_load_dwordx4 v[196:199], v[214:215], off
	global_load_dwordx4 v[200:203], v[214:215], off offset:64
	global_load_dwordx4 v[204:207], v[214:215], off offset:128
	global_load_dwordx4 v[208:211], v[214:215], off offset:192
	v_lshlrev_b64 v[42:43], 11, v[34:35]
	v_lshl_add_u64 v[42:43], s[8:9], 0, v[42:43]
	v_lshl_add_u64 v[42:43], v[116:117], 1, v[42:43]
	s_waitcnt vmcnt(10) lgkmcnt(0)
	v_mov_b32_e32 v36, v180
	v_mov_b32_e32 v37, v181
	v_mov_b32_e32 v38, v182
	v_mov_b32_e32 v39, v183
	v_pk_add_f32 v[30:31], v[30:31], v[36:37]
	v_pk_add_f32 v[32:33], v[32:33], v[38:39]
	v_cvt_pk_bf16_f32 v36, v30, v31
	v_cvt_pk_bf16_f32 v37, v32, v33
	global_store_dwordx4 v[40:41], v[30:33], off
	v_mov_b32_e32 v220, v36
	v_mov_b32_e32 v221, v37
	s_nop 0
	v_pk_mul_f32 v[30:31], v[30:31], v[30:31]
	v_pk_mul_f32 v[32:33], v[32:33], v[32:33]
	v_add_f32_e32 v30, v30, v31
	v_add_f32_e32 v30, v30, v32
	v_add_f32_e32 v30, v30, v33
	s_waitcnt lgkmcnt(0)
	v_mov_b32_e32 v36, v184
	v_mov_b32_e32 v37, v185
	v_mov_b32_e32 v38, v186
	v_mov_b32_e32 v39, v187
	v_pk_add_f32 v[26:27], v[26:27], v[36:37]
	v_pk_add_f32 v[28:29], v[28:29], v[38:39]
	v_cvt_pk_bf16_f32 v36, v26, v27
	v_cvt_pk_bf16_f32 v37, v28, v29
	global_store_dwordx4 v[40:41], v[26:29], off offset:64
	v_mov_b32_e32 v222, v36
	v_mov_b32_e32 v223, v37
	v_mbcnt_lo_u32_b32 v230, -1, 0
	v_mbcnt_hi_u32_b32 v230, -1, v230
	v_and_b32_e32 v230, 16, v230
	v_lshrrev_b32_e32 v228, 1, v230
	v_add_u32_e32 v230, v230, v228
	v_mov_b32_e32 v231, 0
	v_lshl_add_u64 v[228:229], v[42:43], 0, v[230:231]
	v_permlane16_swap_b32_e32 v220, v222
	v_permlane16_swap_b32_e32 v221, v223
	global_store_dwordx4 v[228:229], v[220:223], off
	s_nop 0
	v_pk_mul_f32 v[26:27], v[26:27], v[26:27]
	v_pk_mul_f32 v[28:29], v[28:29], v[28:29]
	v_add_f32_e32 v26, v26, v27
	v_add_f32_e32 v26, v26, v28
	v_add_f32_e32 v26, v26, v29
	v_add_f32_e32 v26, v30, v26
	s_waitcnt lgkmcnt(0)
	v_mov_b32_e32 v36, v188
	v_mov_b32_e32 v37, v189
	v_mov_b32_e32 v38, v190
	v_mov_b32_e32 v39, v191
	v_pk_add_f32 v[22:23], v[22:23], v[36:37]
	v_pk_add_f32 v[24:25], v[24:25], v[38:39]
	v_cvt_pk_bf16_f32 v36, v22, v23
	v_cvt_pk_bf16_f32 v37, v24, v25
	global_store_dwordx4 v[40:41], v[22:25], off offset:128
	v_mov_b32_e32 v224, v36
	v_mov_b32_e32 v225, v37
	s_nop 0
	v_pk_mul_f32 v[22:23], v[22:23], v[22:23]
	v_pk_mul_f32 v[24:25], v[24:25], v[24:25]
	v_add_f32_e32 v22, v22, v23
	v_add_f32_e32 v22, v22, v24
	v_add_f32_e32 v27, v22, v25
	v_add_f32_e32 v26, v26, v27
	s_waitcnt lgkmcnt(0)
	v_mov_b32_e32 v36, v192
	v_mov_b32_e32 v37, v193
	v_mov_b32_e32 v38, v194
	v_mov_b32_e32 v39, v195
	v_pk_add_f32 v[22:23], v[18:19], v[36:37]
	v_pk_add_f32 v[24:25], v[20:21], v[38:39]
	v_pk_mul_f32 v[18:19], v[22:23], v[22:23]
	v_pk_mul_f32 v[20:21], v[24:25], v[24:25]
	v_add_f32_e32 v18, v18, v19
	v_add_f32_e32 v18, v18, v20
	v_add_f32_e32 v18, v18, v21
	v_add_f32_e32 v18, v26, v18
	ds_bpermute_b32 v19, v120, v18
	v_cvt_pk_bf16_f32 v20, v22, v23
	v_cvt_pk_bf16_f32 v21, v24, v25
	global_store_dwordx4 v[40:41], v[22:25], off offset:192
	v_mov_b32_e32 v226, v20
	v_mov_b32_e32 v227, v21
	s_nop 1
	v_lshl_add_u64 v[228:229], v[42:43], 0, v[230:231]
	v_permlane16_swap_b32_e32 v224, v226
	v_permlane16_swap_b32_e32 v225, v227
	global_store_dwordx4 v[228:229], v[224:227], off offset:64
	s_waitcnt lgkmcnt(0)
	v_add_f32_e32 v18, v18, v19
	ds_bpermute_b32 v19, v121, v18
	s_and_saveexec_b64 s[0:1], vcc
	s_cbranch_execz .LBB0_602
	s_waitcnt lgkmcnt(0)
	v_add_f32_e32 v20, v18, v19
	v_lshl_add_u64 v[18:19], v[34:35], 2, s[10:11]
	global_atomic_add_f32 v[18:19], v20, off
.LBB0_602:
	s_or_b64 exec, exec, s[0:1]
	v_or_b32_e32 v114, 0x70, v114
	s_waitcnt lgkmcnt(0)
	v_lshlrev_b64 v[18:19], 12, v[114:115]
	v_lshl_add_u64 v[18:19], v[130:131], 0, v[18:19]
	v_lshl_add_u64 v[22:23], v[116:117], 2, v[18:19]
	s_nop 0
	v_lshlrev_b64 v[24:25], 11, v[114:115]
	v_lshl_add_u64 v[24:25], s[8:9], 0, v[24:25]
	v_lshl_add_u64 v[24:25], v[116:117], 1, v[24:25]
	s_waitcnt vmcnt(6) lgkmcnt(0)
	v_mov_b32_e32 v18, v196
	v_mov_b32_e32 v19, v197
	v_mov_b32_e32 v20, v198
	v_mov_b32_e32 v21, v199
	v_pk_add_f32 v[14:15], v[14:15], v[18:19]
	v_pk_add_f32 v[16:17], v[16:17], v[20:21]
	v_cvt_pk_bf16_f32 v18, v14, v15
	v_cvt_pk_bf16_f32 v19, v16, v17
	global_store_dwordx4 v[22:23], v[14:17], off
	v_mov_b32_e32 v220, v18
	v_mov_b32_e32 v221, v19
	s_nop 0
	v_pk_mul_f32 v[14:15], v[14:15], v[14:15]
	v_pk_mul_f32 v[16:17], v[16:17], v[16:17]
	v_add_f32_e32 v14, v14, v15
	v_add_f32_e32 v14, v14, v16
	v_add_f32_e32 v14, v14, v17
	s_waitcnt lgkmcnt(0)
	v_mov_b32_e32 v18, v200
	v_mov_b32_e32 v19, v201
	v_mov_b32_e32 v20, v202
	v_mov_b32_e32 v21, v203
	v_pk_add_f32 v[10:11], v[10:11], v[18:19]
	v_pk_add_f32 v[12:13], v[12:13], v[20:21]
	v_cvt_pk_bf16_f32 v18, v10, v11
	v_cvt_pk_bf16_f32 v19, v12, v13
	global_store_dwordx4 v[22:23], v[10:13], off offset:64
	v_mov_b32_e32 v222, v18
	v_mov_b32_e32 v223, v19
	v_mbcnt_lo_u32_b32 v230, -1, 0
	v_mbcnt_hi_u32_b32 v230, -1, v230
	v_and_b32_e32 v230, 16, v230
	v_lshrrev_b32_e32 v228, 1, v230
	v_add_u32_e32 v230, v230, v228
	v_mov_b32_e32 v231, 0
	v_lshl_add_u64 v[228:229], v[24:25], 0, v[230:231]
	v_permlane16_swap_b32_e32 v220, v222
	v_permlane16_swap_b32_e32 v221, v223
	global_store_dwordx4 v[228:229], v[220:223], off
	s_nop 0
	v_pk_mul_f32 v[10:11], v[10:11], v[10:11]
	v_pk_mul_f32 v[12:13], v[12:13], v[12:13]
	v_add_f32_e32 v10, v10, v11
	v_add_f32_e32 v10, v10, v12
	v_add_f32_e32 v10, v10, v13
	v_add_f32_e32 v10, v14, v10
	s_waitcnt lgkmcnt(0)
	v_mov_b32_e32 v18, v204
	v_mov_b32_e32 v19, v205
	v_mov_b32_e32 v20, v206
	v_mov_b32_e32 v21, v207
	v_pk_add_f32 v[6:7], v[6:7], v[18:19]
	v_pk_add_f32 v[8:9], v[8:9], v[20:21]
	v_cvt_pk_bf16_f32 v18, v6, v7
	v_cvt_pk_bf16_f32 v19, v8, v9
	global_store_dwordx4 v[22:23], v[6:9], off offset:128
	v_mov_b32_e32 v224, v18
	v_mov_b32_e32 v225, v19
	s_nop 0
	v_pk_mul_f32 v[6:7], v[6:7], v[6:7]
	v_pk_mul_f32 v[8:9], v[8:9], v[8:9]
	v_add_f32_e32 v6, v6, v7
	v_add_f32_e32 v6, v6, v8
	v_add_f32_e32 v11, v6, v9
	v_add_f32_e32 v10, v10, v11
	s_waitcnt lgkmcnt(0)
	v_mov_b32_e32 v18, v208
	v_mov_b32_e32 v19, v209
	v_mov_b32_e32 v20, v210
	v_mov_b32_e32 v21, v211
	v_pk_add_f32 v[6:7], v[2:3], v[18:19]
	v_pk_add_f32 v[8:9], v[4:5], v[20:21]
	v_pk_mul_f32 v[2:3], v[6:7], v[6:7]
	v_pk_mul_f32 v[4:5], v[8:9], v[8:9]
	v_add_f32_e32 v2, v2, v3
	v_add_f32_e32 v2, v2, v4
	v_add_f32_e32 v2, v2, v5
	v_add_f32_e32 v2, v10, v2
	ds_bpermute_b32 v3, v120, v2
	v_cvt_pk_bf16_f32 v4, v6, v7
	v_cvt_pk_bf16_f32 v5, v8, v9
	global_store_dwordx4 v[22:23], v[6:9], off offset:192
	v_mov_b32_e32 v226, v4
	v_mov_b32_e32 v227, v5
	s_nop 1
	v_lshl_add_u64 v[228:229], v[24:25], 0, v[230:231]
	v_permlane16_swap_b32_e32 v224, v226
	v_permlane16_swap_b32_e32 v225, v227
	global_store_dwordx4 v[228:229], v[224:227], off offset:64
	s_waitcnt lgkmcnt(0)
	v_add_f32_e32 v2, v2, v3
	ds_bpermute_b32 v3, v121, v2
	s_and_saveexec_b64 s[0:1], vcc
	s_cbranch_execz .LBB0_585
	s_waitcnt lgkmcnt(0)
	v_add_f32_e32 v4, v2, v3
	v_lshl_add_u64 v[2:3], v[114:115], 2, s[10:11]
	global_atomic_add_f32 v[2:3], v4, off
	s_branch .LBB0_585

.LBB0_1356:
	s_mul_i32 s43, s1, 0x6000
	s_add_i32 s50, s43, 0xffffa000
	s_cmp_lg_u32 s1, 0
	s_cselect_b32 s50, s50, 0xc000
	v_add_u32_e32 v148, s50, v141
	v_lshl_add_u64 v[144:145], v[136:137], 0, s[48:49]
	v_readfirstlane_b32 s50, v148
	v_add_u32_e32 v149, 0x1000, v148
	v_lshl_add_u64 v[146:147], v[144:145], 0, s[24:25]
	s_mov_b32 m0, s50
	v_readfirstlane_b32 s50, v149
	v_add_u32_e32 v149, 0x2000, v148
	s_waitcnt vmcnt(6)
	s_barrier
	global_load_lds_dwordx4 v[146:147], off
	v_lshl_add_u64 v[146:147], v[144:145], 0, s[26:27]
	s_mov_b32 m0, s50
	v_readfirstlane_b32 s50, v149
	global_load_lds_dwordx4 v[146:147], off
	v_lshl_add_u64 v[146:147], v[144:145], 0, s[28:29]
	s_mov_b32 m0, s50
	v_lshl_add_u64 v[144:145], v[144:145], 0, s[30:31]
	global_load_lds_dwordx4 v[146:147], off
	v_add_u32_e32 v146, 0x3000, v148
	v_add_u32_e32 v149, 0x4000, v148
	v_readfirstlane_b32 s50, v146
	s_mov_b32 m0, s50
	v_readfirstlane_b32 s50, v149
	global_load_lds_dwordx4 v[144:145], off
	v_lshl_add_u64 v[144:145], v[134:135], 0, s[48:49]
	v_lshl_add_u64 v[146:147], v[144:145], 0, s[34:35]
	s_mov_b32 m0, s50
	v_lshl_add_u64 v[144:145], v[144:145], 0, s[44:45]
	global_load_lds_dwordx4 v[146:147], off
	v_add_u32_e32 v146, 0x5000, v148
	s_add_i32 s43, s43, 0
	v_readfirstlane_b32 s50, v146
	s_mov_b32 m0, s50
	v_add3_u32 v156, s43, v140, v143
	global_load_lds_dwordx4 v[144:145], off
	v_add3_u32 v176, s43, v142, v143
	ds_read_b128 v[144:147], v156 offset:16384
	ds_read_b128 v[148:151], v156 offset:17408
	ds_read_b128 v[152:155], v156 offset:18432
	ds_read_b128 v[156:159], v156 offset:19456
	ds_read_b128 v[160:163], v176
	ds_read_b128 v[164:167], v176 offset:1024
	ds_read_b128 v[168:171], v176 offset:2048
	ds_read_b128 v[172:175], v176 offset:3072
	s_setprio 1
	s_waitcnt lgkmcnt(0)
	v_mfma_f32_16x16x32_bf16 v[126:129], v[144:147], v[160:163], v[126:129]
	v_mfma_f32_16x16x32_bf16 v[122:125], v[148:151], v[160:163], v[122:125]
	v_mfma_f32_16x16x32_bf16 v[118:121], v[152:155], v[160:163], v[118:121]
	v_mfma_f32_16x16x32_bf16 v[114:117], v[156:159], v[160:163], v[114:117]
	v_mfma_f32_16x16x32_bf16 v[110:113], v[144:147], v[164:167], v[110:113]
	v_mfma_f32_16x16x32_bf16 v[106:109], v[148:151], v[164:167], v[106:109]
	v_mfma_f32_16x16x32_bf16 v[102:105], v[152:155], v[164:167], v[102:105]
	v_mfma_f32_16x16x32_bf16 v[98:101], v[156:159], v[164:167], v[98:101]
	v_mfma_f32_16x16x32_bf16 v[94:97], v[144:147], v[168:171], v[94:97]
	v_mfma_f32_16x16x32_bf16 v[90:93], v[148:151], v[168:171], v[90:93]
	v_mfma_f32_16x16x32_bf16 v[86:89], v[152:155], v[168:171], v[86:89]
	v_mfma_f32_16x16x32_bf16 v[82:85], v[156:159], v[168:171], v[82:85]
	v_mfma_f32_16x16x32_bf16 v[78:81], v[144:147], v[172:175], v[78:81]
	v_mfma_f32_16x16x32_bf16 v[74:77], v[148:151], v[172:175], v[74:77]
	v_mfma_f32_16x16x32_bf16 v[70:73], v[152:155], v[172:175], v[70:73]
	v_mfma_f32_16x16x32_bf16 v[66:69], v[156:159], v[172:175], v[66:69]
	s_setprio 0
	ds_read_b128 v[160:163], v176 offset:4096
	ds_read_b128 v[164:167], v176 offset:5120
	ds_read_b128 v[168:171], v176 offset:6144
	ds_read_b128 v[172:175], v176 offset:7168
	s_setprio 1
	s_waitcnt lgkmcnt(0)
	v_mfma_f32_16x16x32_bf16 v[62:65], v[144:147], v[160:163], v[62:65]
	v_mfma_f32_16x16x32_bf16 v[58:61], v[148:151], v[160:163], v[58:61]
	v_mfma_f32_16x16x32_bf16 v[54:57], v[152:155], v[160:163], v[54:57]
	v_mfma_f32_16x16x32_bf16 v[50:53], v[156:159], v[160:163], v[50:53]
	v_mfma_f32_16x16x32_bf16 v[46:49], v[144:147], v[164:167], v[46:49]
	v_mfma_f32_16x16x32_bf16 v[42:45], v[148:151], v[164:167], v[42:45]
	v_mfma_f32_16x16x32_bf16 v[38:41], v[152:155], v[164:167], v[38:41]
	v_mfma_f32_16x16x32_bf16 v[34:37], v[156:159], v[164:167], v[34:37]
	v_mfma_f32_16x16x32_bf16 v[30:33], v[144:147], v[168:171], v[30:33]
	v_mfma_f32_16x16x32_bf16 v[26:29], v[148:151], v[168:171], v[26:29]
	v_mfma_f32_16x16x32_bf16 v[22:25], v[152:155], v[168:171], v[22:25]
	v_mfma_f32_16x16x32_bf16 v[18:21], v[156:159], v[168:171], v[18:21]
	v_mfma_f32_16x16x32_bf16 v[14:17], v[144:147], v[172:175], v[14:17]
	v_mfma_f32_16x16x32_bf16 v[10:13], v[148:151], v[172:175], v[10:13]
	v_mfma_f32_16x16x32_bf16 v[6:9], v[152:155], v[172:175], v[6:9]
	v_mfma_f32_16x16x32_bf16 v[2:5], v[156:159], v[172:175], v[2:5]
	s_setprio 0
	s_add_i32 s43, s1, 1
	s_cmp_lg_u32 s1, 2
	s_cselect_b32 s1, s43, 0
	s_add_u32 s48, s48, 64
	s_addc_u32 s49, s49, 0
	s_cmpk_eq_i32 s48, 0x780
	s_cbranch_scc0 .LBB0_1356
	v_add3_u32 v168, 0, v140, v143
	v_add3_u32 v169, 0, v142, v143
	s_waitcnt vmcnt(6)
	s_barrier
	ds_read_b128 v[134:137], v168 offset:16384
	ds_read_b128 v[144:147], v168 offset:17408
	ds_read_b128 v[148:151], v168 offset:18432
	ds_read_b128 v[152:155], v168 offset:19456
	ds_read_b128 v[140:143], v169
	ds_read_b128 v[156:159], v169 offset:1024
	ds_read_b128 v[160:163], v169 offset:2048
	ds_read_b128 v[164:167], v169 offset:3072
	s_lshl_b64 s[46:47], s[46:47], 8
	s_setprio 1
	s_waitcnt lgkmcnt(0)
	v_mfma_f32_16x16x32_bf16 v[118:121], v[148:151], v[140:143], v[118:121]
	v_mfma_f32_16x16x32_bf16 v[114:117], v[152:155], v[140:143], v[114:117]
	v_mfma_f32_16x16x32_bf16 v[110:113], v[134:137], v[156:159], v[110:113]
	v_mfma_f32_16x16x32_bf16 v[106:109], v[144:147], v[156:159], v[106:109]
	v_mfma_f32_16x16x32_bf16 v[102:105], v[148:151], v[156:159], v[102:105]
	v_mfma_f32_16x16x32_bf16 v[98:101], v[152:155], v[156:159], v[98:101]
	v_mfma_f32_16x16x32_bf16 v[94:97], v[134:137], v[160:163], v[94:97]
	v_mfma_f32_16x16x32_bf16 v[90:93], v[144:147], v[160:163], v[90:93]
	v_mfma_f32_16x16x32_bf16 v[86:89], v[148:151], v[160:163], v[86:89]
	v_mfma_f32_16x16x32_bf16 v[82:85], v[152:155], v[160:163], v[82:85]
	v_mfma_f32_16x16x32_bf16 v[78:81], v[134:137], v[164:167], v[78:81]
	v_mfma_f32_16x16x32_bf16 v[74:77], v[144:147], v[164:167], v[74:77]
	v_mfma_f32_16x16x32_bf16 v[70:73], v[148:151], v[164:167], v[70:73]
	v_mfma_f32_16x16x32_bf16 v[66:69], v[152:155], v[164:167], v[66:69]
	v_mfma_f32_16x16x32_bf16 v[126:129], v[134:137], v[140:143], v[126:129]
	v_mfma_f32_16x16x32_bf16 v[122:125], v[144:147], v[140:143], v[122:125]
	s_setprio 0
	ds_read_b128 v[140:143], v169 offset:4096
	ds_read_b128 v[156:159], v169 offset:5120
	ds_read_b128 v[160:163], v169 offset:6144
	ds_read_b128 v[164:167], v169 offset:7168
	s_setprio 1
	s_waitcnt lgkmcnt(0)
	v_mfma_f32_16x16x32_bf16 v[62:65], v[134:137], v[140:143], v[62:65]
	v_mfma_f32_16x16x32_bf16 v[58:61], v[144:147], v[140:143], v[58:61]
	v_mfma_f32_16x16x32_bf16 v[54:57], v[148:151], v[140:143], v[54:57]
	v_mfma_f32_16x16x32_bf16 v[50:53], v[152:155], v[140:143], v[50:53]
	v_mfma_f32_16x16x32_bf16 v[46:49], v[134:137], v[156:159], v[46:49]
	v_mfma_f32_16x16x32_bf16 v[42:45], v[144:147], v[156:159], v[42:45]
	v_mfma_f32_16x16x32_bf16 v[38:41], v[148:151], v[156:159], v[38:41]
	v_mfma_f32_16x16x32_bf16 v[34:37], v[152:155], v[156:159], v[34:37]
	v_mfma_f32_16x16x32_bf16 v[30:33], v[134:137], v[160:163], v[30:33]
	v_mfma_f32_16x16x32_bf16 v[26:29], v[144:147], v[160:163], v[26:29]
	v_mfma_f32_16x16x32_bf16 v[22:25], v[148:151], v[160:163], v[22:25]
	v_mfma_f32_16x16x32_bf16 v[18:21], v[152:155], v[160:163], v[18:21]
	v_mfma_f32_16x16x32_bf16 v[14:17], v[134:137], v[164:167], v[14:17]
	v_mfma_f32_16x16x32_bf16 v[10:13], v[144:147], v[164:167], v[10:13]
	v_mfma_f32_16x16x32_bf16 v[6:9], v[148:151], v[164:167], v[6:9]
	v_mfma_f32_16x16x32_bf16 v[2:5], v[152:155], v[164:167], v[2:5]
	s_setprio 0
	s_waitcnt vmcnt(0)
	s_barrier
	ds_read_b128 v[134:137], v168 offset:40960
	ds_read_b128 v[140:143], v168 offset:41984
	ds_read_b128 v[144:147], v168 offset:43008
	ds_read_b128 v[148:151], v168 offset:44032
	ds_read_b128 v[152:155], v169 offset:24576
	ds_read_b128 v[156:159], v169 offset:25600
	ds_read_b128 v[160:163], v169 offset:26624
	ds_read_b128 v[164:167], v169 offset:27648
	s_setprio 1
	s_waitcnt lgkmcnt(0)
	v_mfma_f32_16x16x32_bf16 v[118:121], v[144:147], v[152:155], v[118:121]
	v_mfma_f32_16x16x32_bf16 v[110:113], v[134:137], v[156:159], v[110:113]
	v_mfma_f32_16x16x32_bf16 v[106:109], v[140:143], v[156:159], v[106:109]
	v_mfma_f32_16x16x32_bf16 v[102:105], v[144:147], v[156:159], v[102:105]
	v_mfma_f32_16x16x32_bf16 v[98:101], v[148:151], v[156:159], v[98:101]
	v_mfma_f32_16x16x32_bf16 v[94:97], v[134:137], v[160:163], v[94:97]
	v_mfma_f32_16x16x32_bf16 v[90:93], v[140:143], v[160:163], v[90:93]
	v_mfma_f32_16x16x32_bf16 v[86:89], v[144:147], v[160:163], v[86:89]
	v_mfma_f32_16x16x32_bf16 v[82:85], v[148:151], v[160:163], v[82:85]
	v_mfma_f32_16x16x32_bf16 v[78:81], v[134:137], v[164:167], v[78:81]
	v_mfma_f32_16x16x32_bf16 v[74:77], v[140:143], v[164:167], v[74:77]
	v_mfma_f32_16x16x32_bf16 v[70:73], v[144:147], v[164:167], v[70:73]
	v_mfma_f32_16x16x32_bf16 v[66:69], v[148:151], v[164:167], v[66:69]
	v_mfma_f32_16x16x32_bf16 v[126:129], v[134:137], v[152:155], v[126:129]
	v_mfma_f32_16x16x32_bf16 v[122:125], v[140:143], v[152:155], v[122:125]
	v_mfma_f32_16x16x32_bf16 v[152:155], v[148:151], v[152:155], v[114:117]
	s_setprio 0
	s_nop 1
	ds_read_b128 v[114:117], v169 offset:28672
	ds_read_b128 v[156:159], v169 offset:29696
	ds_read_b128 v[160:163], v169 offset:30720
	ds_read_b128 v[164:167], v169 offset:31744
	s_setprio 1
	s_waitcnt lgkmcnt(0)
	v_mfma_f32_16x16x32_bf16 v[62:65], v[134:137], v[114:117], v[62:65]
	v_mfma_f32_16x16x32_bf16 v[58:61], v[140:143], v[114:117], v[58:61]
	v_mfma_f32_16x16x32_bf16 v[54:57], v[144:147], v[114:117], v[54:57]
	v_mfma_f32_16x16x32_bf16 v[50:53], v[148:151], v[114:117], v[50:53]
	v_mfma_f32_16x16x32_bf16 v[46:49], v[134:137], v[156:159], v[46:49]
	v_mfma_f32_16x16x32_bf16 v[42:45], v[140:143], v[156:159], v[42:45]
	v_mfma_f32_16x16x32_bf16 v[38:41], v[144:147], v[156:159], v[38:41]
	v_mfma_f32_16x16x32_bf16 v[34:37], v[148:151], v[156:159], v[34:37]
	v_mfma_f32_16x16x32_bf16 v[30:33], v[134:137], v[160:163], v[30:33]
	v_mfma_f32_16x16x32_bf16 v[26:29], v[140:143], v[160:163], v[26:29]
	v_mfma_f32_16x16x32_bf16 v[22:25], v[144:147], v[160:163], v[22:25]
	v_mfma_f32_16x16x32_bf16 v[18:21], v[148:151], v[160:163], v[18:21]
	v_mfma_f32_16x16x32_bf16 v[14:17], v[134:137], v[164:167], v[14:17]
	v_mfma_f32_16x16x32_bf16 v[10:13], v[140:143], v[164:167], v[10:13]
	v_mfma_f32_16x16x32_bf16 v[6:9], v[144:147], v[164:167], v[6:9]
	v_mfma_f32_16x16x32_bf16 v[2:5], v[148:151], v[164:167], v[2:5]
	s_setprio 0
	v_lshl_add_u64 v[114:115], s[46:47], 0, v[132:133]
	v_lshl_or_b32 v116, s0, 7, v138
	v_lshlrev_b64 v[134:135], 12, v[114:115]
	s_waitcnt vmcnt(0)
	v_lshl_add_u64 v[134:135], v[130:131], 0, v[134:135]
	v_ashrrev_i32_e32 v117, 31, v116
	v_lshl_add_u64 v[144:145], v[116:117], 2, v[134:135]
	s_barrier
	v_mov_b32_e32 v212, v144
	v_mov_b32_e32 v213, v145
	global_load_dwordx4 v[180:183], v[212:213], off
	global_load_dwordx4 v[184:187], v[212:213], off offset:64
	global_load_dwordx4 v[188:191], v[212:213], off offset:128
	global_load_dwordx4 v[192:195], v[212:213], off offset:192
	s_mov_b32 s98, 0x10000
	s_mov_b32 s99, 0
	v_lshl_add_u64 v[214:215], v[212:213], 0, s[98:99]
	global_load_dwordx4 v[196:199], v[214:215], off
	global_load_dwordx4 v[200:203], v[214:215], off offset:64
	global_load_dwordx4 v[204:207], v[214:215], off offset:128
	global_load_dwordx4 v[208:211], v[214:215], off offset:192
	v_lshlrev_b64 v[140:141], 11, v[114:115]
	v_lshl_add_u64 v[140:141], s[8:9], 0, v[140:141]
	v_lshl_add_u64 v[146:147], v[116:117], 1, v[140:141]
	s_waitcnt vmcnt(4) lgkmcnt(0)
	v_mov_b32_e32 v134, v180
	v_mov_b32_e32 v135, v181
	v_mov_b32_e32 v136, v182
	v_mov_b32_e32 v137, v183
	v_pk_add_f32 v[126:127], v[126:127], v[134:135]
	v_pk_add_f32 v[128:129], v[128:129], v[136:137]
	v_cvt_pk_bf16_f32 v134, v126, v127
	v_cvt_pk_bf16_f32 v135, v128, v129
	global_store_dwordx4 v[144:145], v[126:129], off
	v_mov_b32_e32 v220, v134
	v_mov_b32_e32 v221, v135
	s_nop 0
	s_waitcnt lgkmcnt(0)
	v_mov_b32_e32 v134, v184
	v_mov_b32_e32 v135, v185
	v_mov_b32_e32 v136, v186
	v_mov_b32_e32 v137, v187
	v_pk_add_f32 v[122:123], v[122:123], v[134:135]
	v_pk_add_f32 v[124:125], v[124:125], v[136:137]
	v_cvt_pk_bf16_f32 v134, v122, v123
	v_cvt_pk_bf16_f32 v135, v124, v125
	global_store_dwordx4 v[144:145], v[122:125], off offset:64
	v_mov_b32_e32 v222, v134
	v_mov_b32_e32 v223, v135
	v_mbcnt_lo_u32_b32 v230, -1, 0
	v_mbcnt_hi_u32_b32 v230, -1, v230
	v_and_b32_e32 v230, 16, v230
	v_lshrrev_b32_e32 v228, 1, v230
	v_add_u32_e32 v230, v230, v228
	v_mov_b32_e32 v231, 0
	v_lshl_add_u64 v[228:229], v[146:147], 0, v[230:231]
	v_permlane16_swap_b32_e32 v220, v222
	v_permlane16_swap_b32_e32 v221, v223
	global_store_dwordx4 v[228:229], v[220:223], off
	s_nop 0
	s_waitcnt lgkmcnt(0)
	v_mov_b32_e32 v134, v188
	v_mov_b32_e32 v135, v189
	v_mov_b32_e32 v136, v190
	v_mov_b32_e32 v137, v191
	v_pk_add_f32 v[134:135], v[118:119], v[134:135]
	v_pk_add_f32 v[136:137], v[120:121], v[136:137]
	v_cvt_pk_bf16_f32 v118, v134, v135
	v_cvt_pk_bf16_f32 v119, v136, v137
	global_store_dwordx4 v[144:145], v[134:137], off offset:128
	v_mov_b32_e32 v224, v118
	v_mov_b32_e32 v225, v119
	s_nop 0
	v_and_b32_e32 v119, 64, v139
	v_xor_b32_e32 v118, 16, v139
	v_add_u32_e32 v121, 64, v119
	v_cmp_lt_i32_e64 s[0:1], v118, v121
	s_nop 1
	v_cndmask_b32_e64 v118, v139, v118, s[0:1]
	v_lshlrev_b32_e32 v120, 2, v118
	v_pk_mul_f32 v[118:119], v[126:127], v[126:127]
	v_pk_mul_f32 v[126:127], v[128:129], v[128:129]
	v_add_f32_e32 v118, v118, v119
	v_add_f32_e32 v118, v118, v126
	v_add_f32_e32 v126, v118, v127
	v_pk_mul_f32 v[118:119], v[122:123], v[122:123]
	v_pk_mul_f32 v[122:123], v[124:125], v[124:125]
	v_add_f32_e32 v118, v118, v119
	v_add_f32_e32 v118, v118, v122
	v_add_f32_e32 v118, v118, v123
	v_add_f32_e32 v128, v126, v118
	v_pk_mul_f32 v[118:119], v[134:135], v[134:135]
	v_pk_mul_f32 v[122:123], v[136:137], v[136:137]
	v_add_f32_e32 v118, v118, v119
	v_add_f32_e32 v118, v118, v122
	v_add_f32_e32 v129, v118, v123
	v_add_f32_e32 v128, v128, v129
	s_waitcnt lgkmcnt(0)
	v_mov_b32_e32 v140, v192
	v_mov_b32_e32 v141, v193
	v_mov_b32_e32 v142, v194
	v_mov_b32_e32 v143, v195
	v_pk_add_f32 v[122:123], v[152:153], v[140:141]
	v_pk_add_f32 v[124:125], v[154:155], v[142:143]
	v_pk_mul_f32 v[118:119], v[122:123], v[122:123]
	v_pk_mul_f32 v[126:127], v[124:125], v[124:125]
	v_add_f32_e32 v118, v118, v119
	v_add_f32_e32 v118, v118, v126
	v_add_f32_e32 v118, v118, v127
	v_add_f32_e32 v118, v128, v118
	ds_bpermute_b32 v119, v120, v118
	v_xor_b32_e32 v126, 32, v139
	v_cmp_lt_i32_e64 s[0:1], v126, v121
	global_store_dwordx4 v[144:145], v[122:125], off offset:192
	s_waitcnt lgkmcnt(0)
	v_add_f32_e32 v118, v118, v119
	v_cndmask_b32_e64 v121, v139, v126, s[0:1]
	v_lshlrev_b32_e32 v121, 2, v121
	ds_bpermute_b32 v119, v121, v118
	v_cvt_pk_bf16_f32 v122, v122, v123
	v_cvt_pk_bf16_f32 v123, v124, v125
	v_mov_b32_e32 v226, v122
	v_mov_b32_e32 v227, v123
	s_nop 1
	v_lshl_add_u64 v[228:229], v[146:147], 0, v[230:231]
	v_permlane16_swap_b32_e32 v224, v226
	v_permlane16_swap_b32_e32 v225, v227
	global_store_dwordx4 v[228:229], v[224:227], off offset:64
	s_and_saveexec_b64 s[0:1], vcc
	s_cbranch_execz .LBB0_1359
	s_waitcnt lgkmcnt(0)
	v_add_f32_e32 v122, v118, v119
	v_lshl_add_u64 v[118:119], v[114:115], 2, s[10:11]
	global_atomic_add_f32 v[118:119], v122, off
